# gates GEMM epilogue: the 15 later x loads and the second-half parameter loads of each tile hoisted to the top of the epilogue block into free registers, flat accesses turned into global ones, per-grou
# baseline (speedup 1.0000x reference)
; DI unsigned pk2(float a, float b) { f32x2 v = {a, b}; bf16v2_t r = __builtin_convertvector(v, bf16v2_t); return __builtin_bit_cast(unsigned, r); }
; DI float sigm(float x) { return 1.f / (1.f + __expf(-x)); }
;     DI void operator()(const Acc& acc, const Unit& u, int wr, int wc, int fr, int fq, const float (&pre)[8]) const {
;         const int row0 = u.pm * BM + wr * 64 + fr, f0 = (u.pn >> 1) * 256 + (u.pn & 1) * 128 + wc * 32 + 8 * fq;
; #pragma unroll
;         for (int n = 0; n < 2; ++n) {
;             const f32x4 br = *(const f32x4*)(brg + f0 + 4 * n), bi = *(const f32x4*)(big + f0 + 4 * n), sp = *(const f32x4*)(sp8t + f0 + 4 * n);
; #pragma unroll
;             for (int ai = 0; ai < 2; ++ai)
; #pragma unroll
;                 for (int m = 0; m < 4; ++m) { const size_t o = (size_t)(row0 + ai * HALF + m * 16) * DM + f0 + 4 * n;
;                     const u32x2 xw = *(const u32x2*)(xc + o);
;                     const float xv[4] = {__uint_as_float(xw.x << 16), __uint_as_float(xw.x & 0xffff0000u), __uint_as_float(xw.y << 16), __uint_as_float(xw.y & 0xffff0000u)};
;                     u32x4 w;
; #pragma unroll
;                     for (int e = 0; e < 4; ++e) { const float r = sigm(acc[ai][0][m][n][e] + br[e]), ig = sigm(acc[ai][1][m][n][e] + bi[e]);
;                         const float la = -sp[e] * r, uu = -2.f * la;
;                         const float om = uu * (1.f - uu * 0.5f * (1.f - uu * (1.f / 3.f) * (1.f - uu * 0.25f * (1.f - uu * 0.2f * (1.f - uu * (1.f / 6.f))))));
;                         w[e] = pk2(la, sqrtf(fmaxf(om, 0.f)) * ig * xv[e]); }
;                     *(u32x4*)(ax + o) = w; __builtin_amdgcn_sched_barrier(0); }
.LBB0_944:
	v_lshl_or_b32 v160, s84, 7, v176
	v_ashrrev_i32_e32 v161, 31, v160
	v_lshlrev_b64 v[88:89], 2, v[160:161]
	s_waitcnt lgkmcnt(0)
	v_lshl_add_u64 v[162:163], s[28:29], 0, v[88:89]
	global_load_dwordx4 v[96:99], v[162:163], off
	v_lshl_add_u64 v[164:165], s[30:31], 0, v[88:89]
	global_load_dwordx4 v[92:95], v[164:165], off
	v_lshl_add_u32 v170, s12, 8, v174
	v_ashrrev_i32_e32 v171, 31, v170
	v_lshlrev_b64 v[166:167], 11, v[170:171]
	v_lshl_add_u64 v[172:173], v[166:167], 0, v[160:161]
	v_lshl_add_u64 v[90:91], v[172:173], 1, s[16:17]
	global_load_dwordx2 v[184:185], v[90:91], off
	v_lshl_add_u64 v[168:169], s[34:35], 0, v[88:89]
	global_load_dwordx4 v[88:91], v[168:169], off
	global_load_dwordx4 v[232:235], v[162:163], off offset:16
	global_load_dwordx4 v[236:239], v[164:165], off offset:16
	global_load_dwordx4 v[240:243], v[168:169], off offset:16
	v_lshl_add_u32 v226, s12, 8, v174
	v_lshl_or_b32 v227, s84, 7, v176
	v_lshlrev_b32_e32 v226, 12, v226
	v_lshl_add_u32 v226, v227, 1, v226
	v_add_u32_e32 v227, 0x10000, v226
	global_load_dwordx2 v[196:197], v227, s[16:17]
	v_add_u32_e32 v228, 0x20000, v226
	global_load_dwordx2 v[198:199], v228, s[16:17]
	v_add_u32_e32 v227, 0x30000, v226
	global_load_dwordx2 v[200:201], v227, s[16:17]
	v_add_u32_e32 v228, 0x80000, v226
	global_load_dwordx2 v[202:203], v228, s[16:17]
	v_add_u32_e32 v227, 0x90000, v226
	global_load_dwordx2 v[204:205], v227, s[16:17]
	v_add_u32_e32 v228, 0xa0000, v226
	global_load_dwordx2 v[206:207], v228, s[16:17]
	v_add_u32_e32 v227, 0xb0000, v226
	global_load_dwordx2 v[208:209], v227, s[16:17]
	global_load_dwordx2 v[210:211], v226, s[16:17] offset:8
	v_add_u32_e32 v227, 0x10000, v226
	global_load_dwordx2 v[212:213], v227, s[16:17] offset:8
	v_add_u32_e32 v228, 0x20000, v226
	global_load_dwordx2 v[214:215], v228, s[16:17] offset:8
	v_add_u32_e32 v227, 0x30000, v226
	global_load_dwordx2 v[216:217], v227, s[16:17] offset:8
	v_add_u32_e32 v228, 0x80000, v226
	global_load_dwordx2 v[218:219], v228, s[16:17] offset:8
	v_add_u32_e32 v227, 0x90000, v226
	global_load_dwordx2 v[220:221], v227, s[16:17] offset:8
	v_add_u32_e32 v228, 0xa0000, v226
	global_load_dwordx2 v[222:223], v228, s[16:17] offset:8
	v_add_u32_e32 v227, 0xb0000, v226
	global_load_dwordx2 v[224:225], v227, s[16:17] offset:8
	s_waitcnt vmcnt(18)
	v_add_f32_e32 v136, v136, v96
	v_mul_f32_e32 v136, 0xbfb8aa3b, v136
	v_add_f32_e32 v133, v133, v93
	v_add_f32_e32 v132, v132, v92
	v_mul_f32_e32 v133, 0xbfb8aa3b, v133
	v_exp_f32_e32 v136, v136
	v_add_f32_e32 v137, v137, v97
	v_mul_f32_e32 v132, 0xbfb8aa3b, v132
	v_exp_f32_e32 v133, v133
	v_mul_f32_e32 v137, 0xbfb8aa3b, v137
	v_exp_f32_e32 v132, v132
	v_exp_f32_e32 v137, v137
	v_add_f32_e32 v136, 1.0, v136
	v_add_f32_e32 v190, 1.0, v133
	v_add_f32_e32 v132, 1.0, v132
	v_add_f32_e32 v137, 1.0, v137
	s_waitcnt lgkmcnt(0)
	v_lshlrev_b32_e32 v188, 16, v185
	v_and_b32_e32 v189, 0xffff0000, v185
	v_lshlrev_b32_e32 v171, 16, v184
	v_and_b32_e32 v183, 0xffff0000, v184
	v_rcp_f32_e32 v133, v136
	s_nop 0
	v_mul_f32_e64 v193, v133, -v88
	v_rcp_f32_e32 v192, v132
	v_mul_f32_e32 v132, -2.0, v193
	v_rcp_f32_e32 v136, v137
	v_mul_f32_e32 v133, 0x3e4ccccd, v132
	v_fma_f32 v157, v132, s81, 1.0
	v_mul_f32_e64 v194, v136, -v89
	v_pk_mul_f32 v[136:137], v[132:133], v[156:157]
	v_mul_f32_e32 v159, 0x3eaaaaab, v132
	v_mul_f32_e32 v184, -2.0, v194
	v_sub_f32_e32 v137, 1.0, v137
	v_mov_b32_e32 v133, v159
	v_mul_f32_e32 v186, 0x3eaaaaab, v184
	v_mul_f32_e32 v185, 0x3e4ccccd, v184
	v_fma_f32 v157, v184, s81, 1.0
	v_fma_f32 v159, -v136, v137, 1.0
	v_pk_mul_f32 v[136:137], v[184:185], v[156:157]
	v_mov_b32_e32 v185, v186
	v_pk_mul_f32 v[186:187], v[132:133], v[158:159]
	v_sub_f32_e32 v137, 1.0, v137
	v_sub_f32_e32 v133, 1.0, v187
	v_fma_f32 v133, -v186, v133, 1.0
	v_mul_f32_e32 v132, v132, v133
	v_max_f32_e32 v132, 0, v132
	v_mul_f32_e32 v133, 0x4f800000, v132
	v_cmp_gt_f32_e32 vcc, s82, v132
	v_fma_f32 v159, -v136, v137, 1.0
	v_pk_mul_f32 v[136:137], v[184:185], v[158:159]
	v_cndmask_b32_e32 v132, v132, v133, vcc
	v_sqrt_f32_e32 v133, v132
	v_add_f32_e32 v138, v138, v98
	v_mul_f32_e32 v138, 0xbfb8aa3b, v138
	v_exp_f32_e32 v138, v138
	v_add_u32_e32 v157, -1, v133
	v_add_u32_e32 v159, 1, v133
	v_fma_f32 v185, -v157, v133, v132
	v_fma_f32 v186, -v159, v133, v132
	v_cmp_ge_f32_e64 s[12:13], 0, v185
	v_add_f32_e32 v134, v134, v94
	v_mul_f32_e32 v134, 0xbfb8aa3b, v134
	v_cndmask_b32_e64 v133, v133, v157, s[12:13]
	v_cmp_lt_f32_e64 s[12:13], 0, v186
	v_exp_f32_e32 v134, v134
	v_add_f32_e32 v139, v139, v99
	v_cndmask_b32_e64 v133, v133, v159, s[12:13]
	v_mul_f32_e32 v157, 0x37800000, v133
	v_cndmask_b32_e32 v133, v133, v157, vcc
	v_cmp_class_f32_e32 vcc, v132, v182
	v_add_f32_e32 v134, 1.0, v134
	v_mul_f32_e32 v139, 0xbfb8aa3b, v139
	v_cndmask_b32_e32 v132, v133, v132, vcc
	v_sub_f32_e32 v133, 1.0, v137
	v_fma_f32 v133, -v136, v133, 1.0
	v_mul_f32_e32 v133, v184, v133
	v_max_f32_e32 v133, 0, v133
	v_rcp_f32_e32 v137, v190
	v_mul_f32_e32 v132, v192, v132
	v_mul_f32_e32 v132, v132, v171
	v_exp_f32_e32 v139, v139
	v_add_f32_e32 v135, v135, v95
	v_mul_f32_e32 v135, 0xbfb8aa3b, v135
	v_exp_f32_e32 v135, v135
	v_cvt_pk_bf16_f32 v132, v193, v132
	v_sqrt_f32_e32 v133, v133
	v_add_f32_e32 v136, 1.0, v138
	v_mul_f32_e32 v133, v137, v133
	v_mul_f32_e32 v133, v133, v183
	v_add_f32_e32 v135, 1.0, v135
	v_rcp_f32_e32 v136, v136
	s_nop 0
	v_mul_f32_e64 v186, v136, -v90
	v_mul_f32_e32 v136, -2.0, v186
	v_mul_f32_e32 v137, 0x3e4ccccd, v136
	v_fma_f32 v157, v136, s81, 1.0
	v_pk_mul_f32 v[184:185], v[136:137], v[156:157]
	v_mul_f32_e32 v187, 0x3eaaaaab, v136
	v_sub_f32_e32 v137, 1.0, v185
	v_fma_f32 v159, -v184, v137, 1.0
; DI unsigned pk2(float a, float b) { f32x2 v = {a, b}; bf16v2_t r = __builtin_convertvector(v, bf16v2_t); return __builtin_bit_cast(unsigned, r); }
; DI float sigm(float x) { return 1.f / (1.f + __expf(-x)); }
;     DI void operator()(const Acc& acc, const Unit& u, int wr, int wc, int fr, int fq, const float (&pre)[8]) const {
;     ...
;         for (int n = 0; n < 2; ++n) {
;             const f32x4 br = *(const f32x4*)(brg + f0 + 4 * n), bi = *(const f32x4*)(big + f0 + 4 * n), sp = *(const f32x4*)(sp8t + f0 + 4 * n);
; #pragma unroll
;             for (int ai = 0; ai < 2; ++ai)
; #pragma unroll
;                 for (int m = 0; m < 4; ++m) { const size_t o = (size_t)(row0 + ai * HALF + m * 16) * DM + f0 + 4 * n;
;                     const u32x2 xw = *(const u32x2*)(xc + o);
;                     const float xv[4] = {__uint_as_float(xw.x << 16), __uint_as_float(xw.x & 0xffff0000u), __uint_as_float(xw.y << 16), __uint_as_float(xw.y & 0xffff0000u)};
;                     u32x4 w;
; #pragma unroll
;                     for (int e = 0; e < 4; ++e) { const float r = sigm(acc[ai][0][m][n][e] + br[e]), ig = sigm(acc[ai][1][m][n][e] + bi[e]);
;                         const float la = -sp[e] * r, uu = -2.f * la;
;                         const float om = uu * (1.f - uu * 0.5f * (1.f - uu * (1.f / 3.f) * (1.f - uu * 0.25f * (1.f - uu * 0.2f * (1.f - uu * (1.f / 6.f))))));
;                         w[e] = pk2(la, sqrtf(fmaxf(om, 0.f)) * ig * xv[e]); }
;                     *(u32x4*)(ax + o) = w; __builtin_amdgcn_sched_barrier(0); }
	v_mov_b32_e32 v137, v187
	v_pk_mul_f32 v[184:185], v[136:137], v[158:159]
	v_sub_f32_e32 v137, 1.0, v185
	v_fma_f32 v137, -v184, v137, 1.0
	v_mul_f32_e32 v136, v136, v137
	v_max_f32_e32 v136, 0, v136
	v_rcp_f32_e32 v134, v134
	v_cvt_pk_bf16_f32 v133, v194, v133
	v_sqrt_f32_e32 v136, v136
	v_add_f32_e32 v137, 1.0, v139
	v_mul_f32_e32 v134, v134, v136
	v_mul_f32_e32 v134, v134, v188
	v_cvt_pk_bf16_f32 v134, v186, v134
	v_rcp_f32_e32 v136, v137
	s_nop 0
	v_mul_f32_e64 v185, v136, -v91
	v_mul_f32_e32 v136, -2.0, v185
	v_mul_f32_e32 v137, 0x3e4ccccd, v136
	v_fma_f32 v157, v136, s81, 1.0
	v_pk_mul_f32 v[138:139], v[136:137], v[156:157]
	v_mul_f32_e32 v186, 0x3eaaaaab, v136
	v_sub_f32_e32 v137, 1.0, v139
	v_fma_f32 v159, -v138, v137, 1.0
	v_mov_b32_e32 v137, v186
	v_pk_mul_f32 v[138:139], v[136:137], v[158:159]
	s_nop 0
	v_sub_f32_e32 v137, 1.0, v139
	v_fma_f32 v137, -v138, v137, 1.0
	v_mul_f32_e32 v136, v136, v137
	v_max_f32_e32 v136, 0, v136
	v_rcp_f32_e32 v135, v135
	v_sqrt_f32_e32 v136, v136
	s_nop 0
	v_mul_f32_e32 v135, v135, v136
	v_mul_f32_e32 v135, v135, v189
	v_cvt_pk_bf16_f32 v135, v185, v135
	v_lshl_add_u64 v[136:137], v[172:173], 2, s[36:37]
	global_store_dwordx4 v[136:137], v[132:135], off
	s_nop 1
	v_or_b32_e32 v132, 16, v170
	v_ashrrev_i32_e32 v133, 31, v132
	v_lshlrev_b64 v[132:133], 11, v[132:133]
	v_lshl_add_u64 v[134:135], v[132:133], 0, v[160:161]
	v_lshl_add_u64 v[136:137], v[134:135], 1, s[16:17]
	v_add_f32_e32 v128, v128, v96
	v_add_f32_e32 v129, v129, v97
	v_mul_f32_e32 v128, 0xbfb8aa3b, v128
	v_mul_f32_e32 v129, 0xbfb8aa3b, v129
	v_exp_f32_e32 v128, v128
	v_exp_f32_e32 v129, v129
	v_add_f32_e32 v124, v124, v92
	v_mul_f32_e32 v124, 0xbfb8aa3b, v124
	v_add_f32_e32 v128, 1.0, v128
	v_add_f32_e32 v171, 1.0, v129
	v_exp_f32_e32 v124, v124
	s_nop 0
	v_add_f32_e32 v124, 1.0, v124
	v_rcp_f32_e32 v128, v128
	s_nop 0
	v_mul_f32_e64 v184, v128, -v88
	v_mul_f32_e32 v128, -2.0, v184
	v_mul_f32_e32 v129, 0x3e4ccccd, v128
	v_fma_f32 v157, v128, s81, 1.0
	v_pk_mul_f32 v[138:139], v[128:129], v[156:157]
	v_mul_f32_e32 v159, 0x3eaaaaab, v128
	v_sub_f32_e32 v139, 1.0, v139
	v_mov_b32_e32 v129, v159
	v_fma_f32 v159, -v138, v139, 1.0
	v_pk_mul_f32 v[138:139], v[128:129], v[158:159]
	v_sub_f32_e32 v129, 1.0, v139
	v_fma_f32 v129, -v138, v129, 1.0
	v_mul_f32_e32 v128, v128, v129
	v_max_f32_e32 v128, 0, v128
	v_rcp_f32_e32 v124, v124
	v_add_f32_e32 v125, v125, v93
	v_mul_f32_e32 v125, 0xbfb8aa3b, v125
	v_exp_f32_e32 v125, v125
	s_nop 0
	v_add_f32_e32 v125, 1.0, v125
	v_add_f32_e32 v130, v130, v98
	v_mul_f32_e32 v130, 0xbfb8aa3b, v130
	v_exp_f32_e32 v130, v130
	s_waitcnt vmcnt(15) lgkmcnt(0)
	v_mov_b32_e32 v136, v196
	v_mov_b32_e32 v137, v197
	v_and_b32_e32 v138, 0xffff0000, v136
	v_lshlrev_b32_e32 v139, 16, v137
	v_sqrt_f32_e32 v128, v128
	s_nop 0
	v_mul_f32_e32 v124, v124, v128
	v_lshlrev_b32_e32 v128, 16, v136
	v_mul_f32_e32 v124, v124, v128
	v_rcp_f32_e32 v128, v171
	v_and_b32_e32 v173, 0xffff0000, v137
	v_cvt_pk_bf16_f32 v124, v184, v124
	v_mul_f32_e64 v184, v128, -v89
	v_mul_f32_e32 v128, -2.0, v184
	v_mul_f32_e32 v129, 0x3e4ccccd, v128
	v_fma_f32 v157, v128, s81, 1.0
	v_pk_mul_f32 v[136:137], v[128:129], v[156:157]
	v_mul_f32_e32 v185, 0x3eaaaaab, v128
	v_sub_f32_e32 v129, 1.0, v137
	v_fma_f32 v159, -v136, v129, 1.0
	v_mov_b32_e32 v129, v185
	v_pk_mul_f32 v[136:137], v[128:129], v[158:159]
	v_add_f32_e32 v126, v126, v94
	v_sub_f32_e32 v129, 1.0, v137
	v_fma_f32 v129, -v136, v129, 1.0
	v_mul_f32_e32 v128, v128, v129
	v_max_f32_e32 v128, 0, v128
	v_rcp_f32_e32 v125, v125
	v_mul_f32_e32 v126, 0xbfb8aa3b, v126
	v_exp_f32_e32 v126, v126
	v_add_f32_e32 v131, v131, v99
	v_add_f32_e32 v126, 1.0, v126
	v_mul_f32_e32 v131, 0xbfb8aa3b, v131
	v_exp_f32_e32 v131, v131
	v_add_f32_e32 v127, v127, v95
	v_mul_f32_e32 v127, 0xbfb8aa3b, v127
	v_sqrt_f32_e32 v128, v128
	v_add_f32_e32 v129, 1.0, v130
	v_mul_f32_e32 v125, v125, v128
	v_mul_f32_e32 v125, v125, v138
	v_exp_f32_e32 v127, v127
	v_rcp_f32_e32 v128, v129
	s_nop 0
	v_mul_f32_e64 v172, v128, -v90
	v_mul_f32_e32 v128, -2.0, v172
	v_mul_f32_e32 v129, 0x3e4ccccd, v128
	v_fma_f32 v157, v128, s81, 1.0
	v_pk_mul_f32 v[136:137], v[128:129], v[156:157]
	v_mul_f32_e32 v183, 0x3eaaaaab, v128
	v_sub_f32_e32 v129, 1.0, v137
	v_fma_f32 v159, -v136, v129, 1.0
	v_mov_b32_e32 v129, v183
	v_pk_mul_f32 v[136:137], v[128:129], v[158:159]
	v_sub_f32_e32 v129, 1.0, v137
	v_fma_f32 v129, -v136, v129, 1.0
	v_mul_f32_e32 v128, v128, v129
	v_max_f32_e32 v128, 0, v128
	v_rcp_f32_e32 v126, v126
	v_add_f32_e32 v127, 1.0, v127
	v_cvt_pk_bf16_f32 v125, v184, v125
	v_sqrt_f32_e32 v128, v128
	v_add_f32_e32 v129, 1.0, v131
	v_mul_f32_e32 v126, v126, v128
	v_mul_f32_e32 v126, v126, v139
	v_cvt_pk_bf16_f32 v126, v172, v126
	v_rcp_f32_e32 v128, v129
	s_nop 0
	v_mul_f32_e64 v139, v128, -v91
	v_mul_f32_e32 v128, -2.0, v139
	v_mul_f32_e32 v129, 0x3e4ccccd, v128
	v_fma_f32 v157, v128, s81, 1.0
	v_pk_mul_f32 v[130:131], v[128:129], v[156:157]
	v_mul_f32_e32 v171, 0x3eaaaaab, v128
	v_sub_f32_e32 v129, 1.0, v131
	v_fma_f32 v159, -v130, v129, 1.0
	v_mov_b32_e32 v129, v171
	v_pk_mul_f32 v[130:131], v[128:129], v[158:159]
	s_nop 0
	v_sub_f32_e32 v129, 1.0, v131
	v_fma_f32 v129, -v130, v129, 1.0
	v_mul_f32_e32 v128, v128, v129
	v_max_f32_e32 v128, 0, v128
	v_rcp_f32_e32 v127, v127
	v_sqrt_f32_e32 v128, v128
	s_nop 0
	v_mul_f32_e32 v127, v127, v128
	v_mul_f32_e32 v127, v127, v173
	v_cvt_pk_bf16_f32 v127, v139, v127
	v_lshl_add_u64 v[128:129], v[134:135], 2, s[36:37]
	global_store_dwordx4 v[128:129], v[124:127], off
	s_nop 1
	v_or_b32_e32 v124, 32, v170
	v_ashrrev_i32_e32 v125, 31, v124
	v_lshlrev_b64 v[124:125], 11, v[124:125]
	v_lshl_add_u64 v[126:127], v[124:125], 0, v[160:161]
	v_lshl_add_u64 v[128:129], v[126:127], 1, s[16:17]
	v_add_f32_e32 v120, v120, v96
	v_add_f32_e32 v121, v121, v97
	v_mul_f32_e32 v120, 0xbfb8aa3b, v120
	v_add_f32_e32 v116, v116, v92
	v_mul_f32_e32 v121, 0xbfb8aa3b, v121
	v_exp_f32_e32 v120, v120
	v_mul_f32_e32 v116, 0xbfb8aa3b, v116
	v_exp_f32_e32 v121, v121
	v_exp_f32_e32 v116, v116
	v_add_f32_e32 v120, 1.0, v120
	v_add_f32_e32 v134, 1.0, v121
	v_add_f32_e32 v116, 1.0, v116
	v_rcp_f32_e32 v120, v120
	s_nop 0
	v_mul_f32_e64 v136, v120, -v88
	v_mul_f32_e32 v120, -2.0, v136
	v_mul_f32_e32 v121, 0x3e4ccccd, v120
	v_fma_f32 v157, v120, s81, 1.0
	v_pk_mul_f32 v[130:131], v[120:121], v[156:157]
	v_mul_f32_e32 v159, 0x3eaaaaab, v120
	v_sub_f32_e32 v131, 1.0, v131
	v_mov_b32_e32 v121, v159
	v_fma_f32 v159, -v130, v131, 1.0
	v_pk_mul_f32 v[130:131], v[120:121], v[158:159]
	v_sub_f32_e32 v121, 1.0, v131
	v_fma_f32 v121, -v130, v121, 1.0
	v_mul_f32_e32 v120, v120, v121
	v_max_f32_e32 v120, 0, v120
	v_rcp_f32_e32 v116, v116
	v_add_f32_e32 v117, v117, v93
	v_mul_f32_e32 v117, 0xbfb8aa3b, v117
	v_exp_f32_e32 v117, v117
	s_nop 0
	v_add_f32_e32 v117, 1.0, v117
	v_add_f32_e32 v122, v122, v98
	v_mul_f32_e32 v122, 0xbfb8aa3b, v122
	v_exp_f32_e32 v122, v122
	s_waitcnt vmcnt(15) lgkmcnt(0)
; DI unsigned pk2(float a, float b) { f32x2 v = {a, b}; bf16v2_t r = __builtin_convertvector(v, bf16v2_t); return __builtin_bit_cast(unsigned, r); }
; DI float sigm(float x) { return 1.f / (1.f + __expf(-x)); }
;     DI void operator()(const Acc& acc, const Unit& u, int wr, int wc, int fr, int fq, const float (&pre)[8]) const {
;     ...
;                 for (int m = 0; m < 4; ++m) { const size_t o = (size_t)(row0 + ai * HALF + m * 16) * DM + f0 + 4 * n;
;                     const u32x2 xw = *(const u32x2*)(xc + o);
;                     const float xv[4] = {__uint_as_float(xw.x << 16), __uint_as_float(xw.x & 0xffff0000u), __uint_as_float(xw.y << 16), __uint_as_float(xw.y & 0xffff0000u)};
;                     u32x4 w;
; #pragma unroll
;                     for (int e = 0; e < 4; ++e) { const float r = sigm(acc[ai][0][m][n][e] + br[e]), ig = sigm(acc[ai][1][m][n][e] + bi[e]);
;                         const float la = -sp[e] * r, uu = -2.f * la;
;                         const float om = uu * (1.f - uu * 0.5f * (1.f - uu * (1.f / 3.f) * (1.f - uu * 0.25f * (1.f - uu * 0.2f * (1.f - uu * (1.f / 6.f))))));
;                         w[e] = pk2(la, sqrtf(fmaxf(om, 0.f)) * ig * xv[e]); }
;                     *(u32x4*)(ax + o) = w; __builtin_amdgcn_sched_barrier(0); }
	v_mov_b32_e32 v128, v198
	v_mov_b32_e32 v129, v199
	v_and_b32_e32 v130, 0xffff0000, v128
	v_lshlrev_b32_e32 v131, 16, v129
	v_sqrt_f32_e32 v120, v120
	s_nop 0
	v_mul_f32_e32 v116, v116, v120
	v_lshlrev_b32_e32 v120, 16, v128
	v_mul_f32_e32 v116, v116, v120
	v_rcp_f32_e32 v120, v134
	v_and_b32_e32 v137, 0xffff0000, v129
	v_mul_f32_e64 v138, v120, -v89
	v_mul_f32_e32 v120, -2.0, v138
	v_cvt_pk_bf16_f32 v116, v136, v116
	v_mul_f32_e32 v121, 0x3e4ccccd, v120
	v_fma_f32 v157, v120, s81, 1.0
	v_pk_mul_f32 v[128:129], v[120:121], v[156:157]
	v_mul_f32_e32 v139, 0x3eaaaaab, v120
	v_sub_f32_e32 v121, 1.0, v129
	v_fma_f32 v159, -v128, v121, 1.0
	v_mov_b32_e32 v121, v139
	v_pk_mul_f32 v[128:129], v[120:121], v[158:159]
	v_add_f32_e32 v118, v118, v94
	v_sub_f32_e32 v121, 1.0, v129
	v_fma_f32 v121, -v128, v121, 1.0
	v_mul_f32_e32 v120, v120, v121
	v_max_f32_e32 v120, 0, v120
	v_rcp_f32_e32 v117, v117
	v_mul_f32_e32 v118, 0xbfb8aa3b, v118
	v_exp_f32_e32 v118, v118
	v_add_f32_e32 v123, v123, v99
	v_add_f32_e32 v118, 1.0, v118
	v_mul_f32_e32 v123, 0xbfb8aa3b, v123
	v_exp_f32_e32 v123, v123
	v_add_f32_e32 v119, v119, v95
	v_mul_f32_e32 v119, 0xbfb8aa3b, v119
	v_sqrt_f32_e32 v120, v120
	v_add_f32_e32 v121, 1.0, v122
	v_mul_f32_e32 v117, v117, v120
	v_mul_f32_e32 v117, v117, v130
	v_exp_f32_e32 v119, v119
	v_rcp_f32_e32 v120, v121
	s_nop 0
	v_mul_f32_e64 v135, v120, -v90
	v_mul_f32_e32 v120, -2.0, v135
	v_mul_f32_e32 v121, 0x3e4ccccd, v120
	v_fma_f32 v157, v120, s81, 1.0
	v_pk_mul_f32 v[128:129], v[120:121], v[156:157]
	v_mul_f32_e32 v136, 0x3eaaaaab, v120
	v_sub_f32_e32 v121, 1.0, v129
	v_fma_f32 v159, -v128, v121, 1.0
	v_mov_b32_e32 v121, v136
	v_pk_mul_f32 v[128:129], v[120:121], v[158:159]
	v_sub_f32_e32 v121, 1.0, v129
	v_fma_f32 v121, -v128, v121, 1.0
	v_mul_f32_e32 v120, v120, v121
	v_max_f32_e32 v120, 0, v120
	v_rcp_f32_e32 v118, v118
	v_add_f32_e32 v119, 1.0, v119
	v_cvt_pk_bf16_f32 v117, v138, v117
	v_sqrt_f32_e32 v120, v120
	v_add_f32_e32 v121, 1.0, v123
	v_mul_f32_e32 v118, v118, v120
	v_mul_f32_e32 v118, v118, v131
	v_cvt_pk_bf16_f32 v118, v135, v118
	v_rcp_f32_e32 v120, v121
	s_nop 0
	v_mul_f32_e64 v131, v120, -v91
	v_mul_f32_e32 v120, -2.0, v131
	v_mul_f32_e32 v121, 0x3e4ccccd, v120
	v_fma_f32 v157, v120, s81, 1.0
	v_pk_mul_f32 v[122:123], v[120:121], v[156:157]
	v_mul_f32_e32 v134, 0x3eaaaaab, v120
	v_sub_f32_e32 v121, 1.0, v123
	v_fma_f32 v159, -v122, v121, 1.0
	v_mov_b32_e32 v121, v134
	v_pk_mul_f32 v[122:123], v[120:121], v[158:159]
	s_nop 0
	v_sub_f32_e32 v121, 1.0, v123
	v_fma_f32 v121, -v122, v121, 1.0
	v_mul_f32_e32 v120, v120, v121
	v_max_f32_e32 v120, 0, v120
	v_rcp_f32_e32 v119, v119
	v_sqrt_f32_e32 v120, v120
	s_nop 0
	v_mul_f32_e32 v119, v119, v120
	v_mul_f32_e32 v119, v119, v137
	v_cvt_pk_bf16_f32 v119, v131, v119
	v_lshl_add_u64 v[120:121], v[126:127], 2, s[36:37]
	global_store_dwordx4 v[120:121], v[116:119], off
	s_nop 1
	v_or_b32_e32 v116, 48, v170
	v_ashrrev_i32_e32 v117, 31, v116
	v_lshlrev_b64 v[116:117], 11, v[116:117]
	v_lshl_add_u64 v[118:119], v[116:117], 0, v[160:161]
	v_lshl_add_u64 v[120:121], v[118:119], 1, s[16:17]
	v_add_f32_e32 v112, v112, v96
	v_add_f32_e32 v113, v113, v97
	v_mul_f32_e32 v112, 0xbfb8aa3b, v112
	v_mul_f32_e32 v113, 0xbfb8aa3b, v113
	v_exp_f32_e32 v112, v112
	v_exp_f32_e32 v113, v113
	v_add_f32_e32 v108, v108, v92
	v_mul_f32_e32 v108, 0xbfb8aa3b, v108
	v_add_f32_e32 v112, 1.0, v112
	v_add_f32_e32 v126, 1.0, v113
	v_exp_f32_e32 v108, v108
	s_nop 0
	v_add_f32_e32 v108, 1.0, v108
	v_rcp_f32_e32 v112, v112
	s_nop 0
	v_mul_f32_e64 v128, v112, -v88
	v_mul_f32_e32 v112, -2.0, v128
	v_mul_f32_e32 v113, 0x3e4ccccd, v112
	v_fma_f32 v157, v112, s81, 1.0
	v_pk_mul_f32 v[122:123], v[112:113], v[156:157]
	v_mul_f32_e32 v134, 0x3eaaaaab, v112
	v_sub_f32_e32 v123, 1.0, v123
	v_mov_b32_e32 v113, v134
	v_fma_f32 v159, -v122, v123, 1.0
	v_pk_mul_f32 v[122:123], v[112:113], v[158:159]
	v_sub_f32_e32 v113, 1.0, v123
	v_fma_f32 v113, -v122, v113, 1.0
	v_mul_f32_e32 v112, v112, v113
	v_max_f32_e32 v112, 0, v112
	v_rcp_f32_e32 v108, v108
	v_add_f32_e32 v109, v109, v93
	v_mul_f32_e32 v109, 0xbfb8aa3b, v109
	v_exp_f32_e32 v109, v109
	s_nop 0
	v_add_f32_e32 v109, 1.0, v109
	v_add_f32_e32 v114, v114, v98
	v_mul_f32_e32 v114, 0xbfb8aa3b, v114
	v_exp_f32_e32 v114, v114
	s_waitcnt vmcnt(15) lgkmcnt(0)
; DI unsigned pk2(float a, float b) { f32x2 v = {a, b}; bf16v2_t r = __builtin_convertvector(v, bf16v2_t); return __builtin_bit_cast(unsigned, r); }
; DI float sigm(float x) { return 1.f / (1.f + __expf(-x)); }
;     DI void operator()(const Acc& acc, const Unit& u, int wr, int wc, int fr, int fq, const float (&pre)[8]) const {
;     ...
;                 for (int m = 0; m < 4; ++m) { const size_t o = (size_t)(row0 + ai * HALF + m * 16) * DM + f0 + 4 * n;
;                     const u32x2 xw = *(const u32x2*)(xc + o);
;                     const float xv[4] = {__uint_as_float(xw.x << 16), __uint_as_float(xw.x & 0xffff0000u), __uint_as_float(xw.y << 16), __uint_as_float(xw.y & 0xffff0000u)};
;                     u32x4 w;
; #pragma unroll
;                     for (int e = 0; e < 4; ++e) { const float r = sigm(acc[ai][0][m][n][e] + br[e]), ig = sigm(acc[ai][1][m][n][e] + bi[e]);
;                         const float la = -sp[e] * r, uu = -2.f * la;
;                         const float om = uu * (1.f - uu * 0.5f * (1.f - uu * (1.f / 3.f) * (1.f - uu * 0.25f * (1.f - uu * 0.2f * (1.f - uu * (1.f / 6.f))))));
;                         w[e] = pk2(la, sqrtf(fmaxf(om, 0.f)) * ig * xv[e]); }
;                     *(u32x4*)(ax + o) = w; __builtin_amdgcn_sched_barrier(0); }
	v_mov_b32_e32 v120, v200
	v_mov_b32_e32 v121, v201
	v_and_b32_e32 v122, 0xffff0000, v120
	v_lshlrev_b32_e32 v123, 16, v121
	v_sqrt_f32_e32 v112, v112
	s_nop 0
	v_mul_f32_e32 v108, v108, v112
	v_lshlrev_b32_e32 v112, 16, v120
	v_mul_f32_e32 v108, v108, v112
	v_rcp_f32_e32 v112, v126
	v_and_b32_e32 v129, 0xffff0000, v121
	v_mul_f32_e64 v130, v112, -v89
	v_mul_f32_e32 v112, -2.0, v130
	v_cvt_pk_bf16_f32 v108, v128, v108
	v_mul_f32_e32 v113, 0x3e4ccccd, v112
	v_fma_f32 v157, v112, s81, 1.0
	v_pk_mul_f32 v[120:121], v[112:113], v[156:157]
	v_mul_f32_e32 v131, 0x3eaaaaab, v112
	v_sub_f32_e32 v113, 1.0, v121
	v_fma_f32 v159, -v120, v113, 1.0
	v_mov_b32_e32 v113, v131
	v_pk_mul_f32 v[120:121], v[112:113], v[158:159]
	v_add_f32_e32 v110, v110, v94
	v_sub_f32_e32 v113, 1.0, v121
	v_fma_f32 v113, -v120, v113, 1.0
	v_mul_f32_e32 v112, v112, v113
	v_max_f32_e32 v112, 0, v112
	v_rcp_f32_e32 v109, v109
	v_mul_f32_e32 v110, 0xbfb8aa3b, v110
	v_exp_f32_e32 v110, v110
	v_add_f32_e32 v115, v115, v99
	v_add_f32_e32 v110, 1.0, v110
	v_mul_f32_e32 v115, 0xbfb8aa3b, v115
	v_exp_f32_e32 v115, v115
	v_add_f32_e32 v111, v111, v95
	v_mul_f32_e32 v111, 0xbfb8aa3b, v111
	v_sqrt_f32_e32 v112, v112
	v_add_f32_e32 v113, 1.0, v114
	v_mul_f32_e32 v109, v109, v112
	v_mul_f32_e32 v109, v109, v122
	v_exp_f32_e32 v111, v111
	v_rcp_f32_e32 v112, v113
	s_nop 0
	v_mul_f32_e64 v127, v112, -v90
	v_mul_f32_e32 v112, -2.0, v127
	v_mul_f32_e32 v113, 0x3e4ccccd, v112
	v_fma_f32 v157, v112, s81, 1.0
	v_pk_mul_f32 v[120:121], v[112:113], v[156:157]
	v_mul_f32_e32 v128, 0x3eaaaaab, v112
	v_sub_f32_e32 v113, 1.0, v121
	v_fma_f32 v159, -v120, v113, 1.0
	v_mov_b32_e32 v113, v128
	v_pk_mul_f32 v[120:121], v[112:113], v[158:159]
	v_sub_f32_e32 v113, 1.0, v121
	v_fma_f32 v113, -v120, v113, 1.0
	v_mul_f32_e32 v112, v112, v113
	v_max_f32_e32 v112, 0, v112
	v_rcp_f32_e32 v110, v110
	v_add_f32_e32 v111, 1.0, v111
	v_cvt_pk_bf16_f32 v109, v130, v109
	v_sqrt_f32_e32 v112, v112
	v_add_f32_e32 v113, 1.0, v115
	v_mul_f32_e32 v110, v110, v112
	v_mul_f32_e32 v110, v110, v123
	v_cvt_pk_bf16_f32 v110, v127, v110
	v_rcp_f32_e32 v112, v113
	s_nop 0
	v_mul_f32_e64 v123, v112, -v91
	v_mul_f32_e32 v112, -2.0, v123
	v_mul_f32_e32 v113, 0x3e4ccccd, v112
	v_fma_f32 v157, v112, s81, 1.0
	v_pk_mul_f32 v[114:115], v[112:113], v[156:157]
	v_mul_f32_e32 v126, 0x3eaaaaab, v112
	v_sub_f32_e32 v113, 1.0, v115
	v_fma_f32 v159, -v114, v113, 1.0
	v_mov_b32_e32 v113, v126
	v_pk_mul_f32 v[114:115], v[112:113], v[158:159]
	s_nop 0
	v_sub_f32_e32 v113, 1.0, v115
	v_fma_f32 v113, -v114, v113, 1.0
	v_mul_f32_e32 v112, v112, v113
	v_max_f32_e32 v112, 0, v112
	v_rcp_f32_e32 v111, v111
	v_sqrt_f32_e32 v112, v112
	s_nop 0
	v_mul_f32_e32 v111, v111, v112
	v_mul_f32_e32 v111, v111, v129
	v_cvt_pk_bf16_f32 v111, v123, v111
	v_lshl_add_u64 v[112:113], v[118:119], 2, s[36:37]
	global_store_dwordx4 v[112:113], v[108:111], off
	s_nop 1
	v_lshl_add_u64 v[108:109], v[166:167], 0, s[42:43]
	v_lshl_add_u64 v[110:111], v[108:109], 0, v[160:161]
	v_lshl_add_u64 v[112:113], v[110:111], 1, s[16:17]
	v_add_f32_e32 v104, v104, v96
	v_add_f32_e32 v105, v105, v97
	v_mul_f32_e32 v104, 0xbfb8aa3b, v104
	v_mul_f32_e32 v105, 0xbfb8aa3b, v105
	v_exp_f32_e32 v104, v104
	v_exp_f32_e32 v105, v105
	v_add_f32_e32 v100, v100, v92
	v_mul_f32_e32 v100, 0xbfb8aa3b, v100
	v_add_f32_e32 v104, 1.0, v104
	v_add_f32_e32 v118, 1.0, v105
	v_exp_f32_e32 v100, v100
	s_nop 0
	v_add_f32_e32 v100, 1.0, v100
	v_rcp_f32_e32 v104, v104
	s_nop 0
	v_mul_f32_e64 v120, v104, -v88
	v_mul_f32_e32 v104, -2.0, v120
	v_mul_f32_e32 v105, 0x3e4ccccd, v104
	v_fma_f32 v157, v104, s81, 1.0
	v_pk_mul_f32 v[114:115], v[104:105], v[156:157]
	v_mul_f32_e32 v126, 0x3eaaaaab, v104
	v_sub_f32_e32 v115, 1.0, v115
	v_mov_b32_e32 v105, v126
	v_fma_f32 v159, -v114, v115, 1.0
	v_pk_mul_f32 v[114:115], v[104:105], v[158:159]
	v_sub_f32_e32 v105, 1.0, v115
	v_fma_f32 v105, -v114, v105, 1.0
	v_mul_f32_e32 v104, v104, v105
	v_max_f32_e32 v104, 0, v104
	v_rcp_f32_e32 v100, v100
	v_add_f32_e32 v101, v101, v93
	v_mul_f32_e32 v101, 0xbfb8aa3b, v101
	v_exp_f32_e32 v101, v101
	s_nop 0
	v_add_f32_e32 v101, 1.0, v101
	v_add_f32_e32 v106, v106, v98
	v_mul_f32_e32 v106, 0xbfb8aa3b, v106
	v_exp_f32_e32 v106, v106
	s_waitcnt vmcnt(15) lgkmcnt(0)
; DI unsigned pk2(float a, float b) { f32x2 v = {a, b}; bf16v2_t r = __builtin_convertvector(v, bf16v2_t); return __builtin_bit_cast(unsigned, r); }
; DI float sigm(float x) { return 1.f / (1.f + __expf(-x)); }
;     DI void operator()(const Acc& acc, const Unit& u, int wr, int wc, int fr, int fq, const float (&pre)[8]) const {
;     ...
;                 for (int m = 0; m < 4; ++m) { const size_t o = (size_t)(row0 + ai * HALF + m * 16) * DM + f0 + 4 * n;
;                     const u32x2 xw = *(const u32x2*)(xc + o);
;                     const float xv[4] = {__uint_as_float(xw.x << 16), __uint_as_float(xw.x & 0xffff0000u), __uint_as_float(xw.y << 16), __uint_as_float(xw.y & 0xffff0000u)};
;                     u32x4 w;
; #pragma unroll
;                     for (int e = 0; e < 4; ++e) { const float r = sigm(acc[ai][0][m][n][e] + br[e]), ig = sigm(acc[ai][1][m][n][e] + bi[e]);
;                         const float la = -sp[e] * r, uu = -2.f * la;
;                         const float om = uu * (1.f - uu * 0.5f * (1.f - uu * (1.f / 3.f) * (1.f - uu * 0.25f * (1.f - uu * 0.2f * (1.f - uu * (1.f / 6.f))))));
;                         w[e] = pk2(la, sqrtf(fmaxf(om, 0.f)) * ig * xv[e]); }
;                     *(u32x4*)(ax + o) = w; __builtin_amdgcn_sched_barrier(0); }
	v_mov_b32_e32 v112, v202
	v_mov_b32_e32 v113, v203
	v_and_b32_e32 v114, 0xffff0000, v112
	v_lshlrev_b32_e32 v115, 16, v113
	v_sqrt_f32_e32 v104, v104
	s_nop 0
	v_mul_f32_e32 v100, v100, v104
	v_lshlrev_b32_e32 v104, 16, v112
	v_mul_f32_e32 v100, v100, v104
	v_rcp_f32_e32 v104, v118
	v_and_b32_e32 v121, 0xffff0000, v113
	v_mul_f32_e64 v122, v104, -v89
	v_mul_f32_e32 v104, -2.0, v122
	v_cvt_pk_bf16_f32 v100, v120, v100
	v_mul_f32_e32 v105, 0x3e4ccccd, v104
	v_fma_f32 v157, v104, s81, 1.0
	v_pk_mul_f32 v[112:113], v[104:105], v[156:157]
	v_mul_f32_e32 v123, 0x3eaaaaab, v104
	v_sub_f32_e32 v105, 1.0, v113
	v_fma_f32 v159, -v112, v105, 1.0
	v_mov_b32_e32 v105, v123
	v_pk_mul_f32 v[112:113], v[104:105], v[158:159]
	v_add_f32_e32 v102, v102, v94
	v_sub_f32_e32 v105, 1.0, v113
	v_fma_f32 v105, -v112, v105, 1.0
	v_mul_f32_e32 v104, v104, v105
	v_max_f32_e32 v104, 0, v104
	v_rcp_f32_e32 v101, v101
	v_mul_f32_e32 v102, 0xbfb8aa3b, v102
	v_exp_f32_e32 v102, v102
	v_add_f32_e32 v107, v107, v99
	v_add_f32_e32 v102, 1.0, v102
	v_mul_f32_e32 v107, 0xbfb8aa3b, v107
	v_exp_f32_e32 v107, v107
	v_add_f32_e32 v103, v103, v95
	v_mul_f32_e32 v103, 0xbfb8aa3b, v103
	v_sqrt_f32_e32 v104, v104
	v_add_f32_e32 v105, 1.0, v106
	v_mul_f32_e32 v101, v101, v104
	v_mul_f32_e32 v101, v101, v114
	v_exp_f32_e32 v103, v103
	v_rcp_f32_e32 v104, v105
	s_nop 0
	v_mul_f32_e64 v119, v104, -v90
	v_mul_f32_e32 v104, -2.0, v119
	v_mul_f32_e32 v105, 0x3e4ccccd, v104
	v_fma_f32 v157, v104, s81, 1.0
	v_pk_mul_f32 v[112:113], v[104:105], v[156:157]
	v_mul_f32_e32 v120, 0x3eaaaaab, v104
	v_sub_f32_e32 v105, 1.0, v113
	v_fma_f32 v159, -v112, v105, 1.0
	v_mov_b32_e32 v105, v120
	v_pk_mul_f32 v[112:113], v[104:105], v[158:159]
	v_sub_f32_e32 v105, 1.0, v113
	v_fma_f32 v105, -v112, v105, 1.0
	v_mul_f32_e32 v104, v104, v105
	v_max_f32_e32 v104, 0, v104
	v_rcp_f32_e32 v102, v102
	v_add_f32_e32 v103, 1.0, v103
	v_cvt_pk_bf16_f32 v101, v122, v101
	v_sqrt_f32_e32 v104, v104
	v_add_f32_e32 v105, 1.0, v107
	v_mul_f32_e32 v102, v102, v104
	v_mul_f32_e32 v102, v102, v115
	v_cvt_pk_bf16_f32 v102, v119, v102
	v_rcp_f32_e32 v104, v105
	s_nop 0
	v_mul_f32_e64 v115, v104, -v91
	v_mul_f32_e32 v104, -2.0, v115
	v_mul_f32_e32 v105, 0x3e4ccccd, v104
	v_fma_f32 v157, v104, s81, 1.0
	v_pk_mul_f32 v[106:107], v[104:105], v[156:157]
	v_mul_f32_e32 v118, 0x3eaaaaab, v104
	v_sub_f32_e32 v105, 1.0, v107
	v_fma_f32 v159, -v106, v105, 1.0
	v_mov_b32_e32 v105, v118
	v_pk_mul_f32 v[106:107], v[104:105], v[158:159]
	s_nop 0
	v_sub_f32_e32 v105, 1.0, v107
	v_fma_f32 v105, -v106, v105, 1.0
	v_mul_f32_e32 v104, v104, v105
	v_max_f32_e32 v104, 0, v104
	v_rcp_f32_e32 v103, v103
	v_sqrt_f32_e32 v104, v104
	s_nop 0
	v_mul_f32_e32 v103, v103, v104
	v_mul_f32_e32 v103, v103, v121
	v_cvt_pk_bf16_f32 v103, v115, v103
	v_lshl_add_u64 v[104:105], v[110:111], 2, s[36:37]
	global_store_dwordx4 v[104:105], v[100:103], off
	s_nop 1
	v_lshl_add_u64 v[100:101], v[166:167], 0, s[44:45]
	v_lshl_add_u64 v[102:103], v[100:101], 0, v[160:161]
	v_lshl_add_u64 v[104:105], v[102:103], 1, s[16:17]
	v_add_f32_e32 v84, v84, v96
	v_add_f32_e32 v85, v85, v97
	v_mul_f32_e32 v84, 0xbfb8aa3b, v84
	v_mul_f32_e32 v85, 0xbfb8aa3b, v85
	v_exp_f32_e32 v84, v84
	v_exp_f32_e32 v85, v85
	v_add_f32_e32 v80, v80, v92
	v_mul_f32_e32 v80, 0xbfb8aa3b, v80
	v_add_f32_e32 v84, 1.0, v84
	v_add_f32_e32 v110, 1.0, v85
	v_exp_f32_e32 v80, v80
	s_nop 0
	v_add_f32_e32 v80, 1.0, v80
	v_rcp_f32_e32 v84, v84
	s_nop 0
	v_mul_f32_e64 v112, v84, -v88
	v_mul_f32_e32 v84, -2.0, v112
	v_mul_f32_e32 v85, 0x3e4ccccd, v84
	v_fma_f32 v157, v84, s81, 1.0
	v_pk_mul_f32 v[106:107], v[84:85], v[156:157]
	v_mul_f32_e32 v118, 0x3eaaaaab, v84
	v_sub_f32_e32 v107, 1.0, v107
	v_mov_b32_e32 v85, v118
	v_fma_f32 v159, -v106, v107, 1.0
	v_pk_mul_f32 v[106:107], v[84:85], v[158:159]
	v_sub_f32_e32 v85, 1.0, v107
	v_fma_f32 v85, -v106, v85, 1.0
	v_mul_f32_e32 v84, v84, v85
	v_max_f32_e32 v84, 0, v84
	v_rcp_f32_e32 v80, v80
	v_add_f32_e32 v81, v81, v93
	v_mul_f32_e32 v81, 0xbfb8aa3b, v81
	v_exp_f32_e32 v81, v81
	s_nop 0
	v_add_f32_e32 v81, 1.0, v81
	v_add_f32_e32 v86, v86, v98
	v_mul_f32_e32 v86, 0xbfb8aa3b, v86
	v_exp_f32_e32 v86, v86
	s_waitcnt vmcnt(15) lgkmcnt(0)
	v_mov_b32_e32 v104, v204
	v_mov_b32_e32 v105, v205
	v_and_b32_e32 v106, 0xffff0000, v104
	v_lshlrev_b32_e32 v107, 16, v105
	v_sqrt_f32_e32 v84, v84
	s_nop 0
	v_mul_f32_e32 v80, v80, v84
	v_lshlrev_b32_e32 v84, 16, v104
	v_mul_f32_e32 v80, v80, v84
	v_rcp_f32_e32 v84, v110
	v_and_b32_e32 v113, 0xffff0000, v105
	v_mul_f32_e64 v114, v84, -v89
	v_mul_f32_e32 v84, -2.0, v114
	v_cvt_pk_bf16_f32 v80, v112, v80
	v_mul_f32_e32 v85, 0x3e4ccccd, v84
	v_fma_f32 v157, v84, s81, 1.0
	v_pk_mul_f32 v[104:105], v[84:85], v[156:157]
	v_mul_f32_e32 v115, 0x3eaaaaab, v84
	v_sub_f32_e32 v85, 1.0, v105
	v_fma_f32 v159, -v104, v85, 1.0
	v_mov_b32_e32 v85, v115
	v_pk_mul_f32 v[104:105], v[84:85], v[158:159]
	v_add_f32_e32 v82, v82, v94
	v_sub_f32_e32 v85, 1.0, v105
	v_fma_f32 v85, -v104, v85, 1.0
	v_mul_f32_e32 v84, v84, v85
	v_max_f32_e32 v84, 0, v84
	v_rcp_f32_e32 v81, v81
	v_mul_f32_e32 v82, 0xbfb8aa3b, v82
	v_exp_f32_e32 v82, v82
	v_add_f32_e32 v87, v87, v99
	v_add_f32_e32 v82, 1.0, v82
	v_mul_f32_e32 v87, 0xbfb8aa3b, v87
	v_exp_f32_e32 v87, v87
	v_add_f32_e32 v83, v83, v95
	v_mul_f32_e32 v83, 0xbfb8aa3b, v83
	v_sqrt_f32_e32 v84, v84
	v_add_f32_e32 v85, 1.0, v86
	v_mul_f32_e32 v81, v81, v84
	v_mul_f32_e32 v81, v81, v106
	v_exp_f32_e32 v83, v83
	v_rcp_f32_e32 v84, v85
	s_nop 0
	v_mul_f32_e64 v111, v84, -v90
	v_mul_f32_e32 v84, -2.0, v111
	v_mul_f32_e32 v85, 0x3e4ccccd, v84
	v_fma_f32 v157, v84, s81, 1.0
	v_pk_mul_f32 v[104:105], v[84:85], v[156:157]
; DI unsigned pk2(float a, float b) { f32x2 v = {a, b}; bf16v2_t r = __builtin_convertvector(v, bf16v2_t); return __builtin_bit_cast(unsigned, r); }
; DI float sigm(float x) { return 1.f / (1.f + __expf(-x)); }
;     DI void operator()(const Acc& acc, const Unit& u, int wr, int wc, int fr, int fq, const float (&pre)[8]) const {
;     ...
;                 for (int m = 0; m < 4; ++m) { const size_t o = (size_t)(row0 + ai * HALF + m * 16) * DM + f0 + 4 * n;
;                     const u32x2 xw = *(const u32x2*)(xc + o);
;                     const float xv[4] = {__uint_as_float(xw.x << 16), __uint_as_float(xw.x & 0xffff0000u), __uint_as_float(xw.y << 16), __uint_as_float(xw.y & 0xffff0000u)};
;                     u32x4 w;
; #pragma unroll
;                     for (int e = 0; e < 4; ++e) { const float r = sigm(acc[ai][0][m][n][e] + br[e]), ig = sigm(acc[ai][1][m][n][e] + bi[e]);
;                         const float la = -sp[e] * r, uu = -2.f * la;
;                         const float om = uu * (1.f - uu * 0.5f * (1.f - uu * (1.f / 3.f) * (1.f - uu * 0.25f * (1.f - uu * 0.2f * (1.f - uu * (1.f / 6.f))))));
;                         w[e] = pk2(la, sqrtf(fmaxf(om, 0.f)) * ig * xv[e]); }
;                     *(u32x4*)(ax + o) = w; __builtin_amdgcn_sched_barrier(0); }
	v_mul_f32_e32 v112, 0x3eaaaaab, v84
	v_sub_f32_e32 v85, 1.0, v105
	v_fma_f32 v159, -v104, v85, 1.0
	v_mov_b32_e32 v85, v112
	v_pk_mul_f32 v[104:105], v[84:85], v[158:159]
	v_sub_f32_e32 v85, 1.0, v105
	v_fma_f32 v85, -v104, v85, 1.0
	v_mul_f32_e32 v84, v84, v85
	v_max_f32_e32 v84, 0, v84
	v_rcp_f32_e32 v82, v82
	v_add_f32_e32 v83, 1.0, v83
	v_cvt_pk_bf16_f32 v81, v114, v81
	v_sqrt_f32_e32 v84, v84
	v_add_f32_e32 v85, 1.0, v87
	v_mul_f32_e32 v82, v82, v84
	v_mul_f32_e32 v82, v82, v107
	v_cvt_pk_bf16_f32 v82, v111, v82
	v_rcp_f32_e32 v84, v85
	s_nop 0
	v_mul_f32_e64 v107, v84, -v91
	v_mul_f32_e32 v84, -2.0, v107
	v_mul_f32_e32 v85, 0x3e4ccccd, v84
	v_fma_f32 v157, v84, s81, 1.0
	v_pk_mul_f32 v[86:87], v[84:85], v[156:157]
	v_mul_f32_e32 v110, 0x3eaaaaab, v84
	v_sub_f32_e32 v85, 1.0, v87
	v_fma_f32 v159, -v86, v85, 1.0
	v_mov_b32_e32 v85, v110
	v_pk_mul_f32 v[86:87], v[84:85], v[158:159]
	s_nop 0
	v_sub_f32_e32 v85, 1.0, v87
	v_fma_f32 v85, -v86, v85, 1.0
	v_mul_f32_e32 v84, v84, v85
	v_max_f32_e32 v84, 0, v84
	v_rcp_f32_e32 v83, v83
	v_sqrt_f32_e32 v84, v84
	s_nop 0
	v_mul_f32_e32 v83, v83, v84
	v_mul_f32_e32 v83, v83, v113
	v_cvt_pk_bf16_f32 v83, v107, v83
	v_lshl_add_u64 v[84:85], v[102:103], 2, s[36:37]
	global_store_dwordx4 v[84:85], v[80:83], off
	s_nop 1
	v_lshl_add_u64 v[80:81], v[166:167], 0, s[46:47]
	v_lshl_add_u64 v[82:83], v[80:81], 0, v[160:161]
	v_lshl_add_u64 v[84:85], v[82:83], 1, s[16:17]
	v_add_f32_e32 v76, v76, v96
	v_add_f32_e32 v77, v77, v97
	v_mul_f32_e32 v76, 0xbfb8aa3b, v76
	v_mul_f32_e32 v77, 0xbfb8aa3b, v77
	v_exp_f32_e32 v76, v76
	v_exp_f32_e32 v77, v77
	v_add_f32_e32 v72, v72, v92
	v_mul_f32_e32 v72, 0xbfb8aa3b, v72
	v_add_f32_e32 v76, 1.0, v76
	v_add_f32_e32 v102, 1.0, v77
	v_exp_f32_e32 v72, v72
	s_nop 0
	v_add_f32_e32 v72, 1.0, v72
	v_rcp_f32_e32 v76, v76
	s_nop 0
	v_mul_f32_e64 v104, v76, -v88
	v_mul_f32_e32 v76, -2.0, v104
	v_mul_f32_e32 v77, 0x3e4ccccd, v76
	v_fma_f32 v157, v76, s81, 1.0
	v_pk_mul_f32 v[86:87], v[76:77], v[156:157]
	v_mul_f32_e32 v110, 0x3eaaaaab, v76
	v_sub_f32_e32 v87, 1.0, v87
	v_mov_b32_e32 v77, v110
	v_fma_f32 v159, -v86, v87, 1.0
	v_pk_mul_f32 v[86:87], v[76:77], v[158:159]
	v_sub_f32_e32 v77, 1.0, v87
	v_fma_f32 v77, -v86, v77, 1.0
	v_mul_f32_e32 v76, v76, v77
	v_max_f32_e32 v76, 0, v76
	v_rcp_f32_e32 v72, v72
	v_add_f32_e32 v73, v73, v93
	v_mul_f32_e32 v73, 0xbfb8aa3b, v73
	v_exp_f32_e32 v73, v73
	s_nop 0
	v_add_f32_e32 v73, 1.0, v73
	v_add_f32_e32 v78, v78, v98
	v_mul_f32_e32 v78, 0xbfb8aa3b, v78
	v_exp_f32_e32 v78, v78
	s_waitcnt vmcnt(15) lgkmcnt(0)
	v_mov_b32_e32 v84, v206
	v_mov_b32_e32 v85, v207
	v_and_b32_e32 v86, 0xffff0000, v84
	v_lshlrev_b32_e32 v87, 16, v85
	v_sqrt_f32_e32 v76, v76
	s_nop 0
	v_mul_f32_e32 v72, v72, v76
	v_lshlrev_b32_e32 v76, 16, v84
	v_mul_f32_e32 v72, v72, v76
	v_rcp_f32_e32 v76, v102
	v_and_b32_e32 v105, 0xffff0000, v85
	v_mul_f32_e64 v106, v76, -v89
	v_mul_f32_e32 v76, -2.0, v106
	v_cvt_pk_bf16_f32 v72, v104, v72
	v_mul_f32_e32 v77, 0x3e4ccccd, v76
	v_fma_f32 v157, v76, s81, 1.0
	v_pk_mul_f32 v[84:85], v[76:77], v[156:157]
	v_mul_f32_e32 v107, 0x3eaaaaab, v76
	v_sub_f32_e32 v77, 1.0, v85
	v_fma_f32 v159, -v84, v77, 1.0
	v_mov_b32_e32 v77, v107
	v_pk_mul_f32 v[84:85], v[76:77], v[158:159]
	v_add_f32_e32 v74, v74, v94
	v_sub_f32_e32 v77, 1.0, v85
	v_fma_f32 v77, -v84, v77, 1.0
	v_mul_f32_e32 v76, v76, v77
	v_max_f32_e32 v76, 0, v76
	v_rcp_f32_e32 v73, v73
	v_mul_f32_e32 v74, 0xbfb8aa3b, v74
	v_exp_f32_e32 v74, v74
	v_add_f32_e32 v79, v79, v99
	v_add_f32_e32 v74, 1.0, v74
	v_mul_f32_e32 v79, 0xbfb8aa3b, v79
	v_exp_f32_e32 v79, v79
	v_add_f32_e32 v75, v75, v95
	v_mul_f32_e32 v75, 0xbfb8aa3b, v75
	v_sqrt_f32_e32 v76, v76
	v_add_f32_e32 v77, 1.0, v78
	v_mul_f32_e32 v73, v73, v76
	v_mul_f32_e32 v73, v73, v86
	v_exp_f32_e32 v75, v75
	v_rcp_f32_e32 v76, v77
	s_nop 0
	v_mul_f32_e64 v103, v76, -v90
	v_mul_f32_e32 v76, -2.0, v103
	v_mul_f32_e32 v77, 0x3e4ccccd, v76
	v_fma_f32 v157, v76, s81, 1.0
	v_pk_mul_f32 v[84:85], v[76:77], v[156:157]
	v_mul_f32_e32 v104, 0x3eaaaaab, v76
	v_sub_f32_e32 v77, 1.0, v85
	v_fma_f32 v159, -v84, v77, 1.0
	v_mov_b32_e32 v77, v104
	v_pk_mul_f32 v[84:85], v[76:77], v[158:159]
	v_sub_f32_e32 v77, 1.0, v85
	v_fma_f32 v77, -v84, v77, 1.0
	v_mul_f32_e32 v76, v76, v77
	v_max_f32_e32 v76, 0, v76
	v_rcp_f32_e32 v74, v74
	v_add_f32_e32 v75, 1.0, v75
	v_cvt_pk_bf16_f32 v73, v106, v73
	v_sqrt_f32_e32 v76, v76
	v_add_f32_e32 v77, 1.0, v79
	v_mul_f32_e32 v74, v74, v76
	v_mul_f32_e32 v74, v74, v87
	v_cvt_pk_bf16_f32 v74, v103, v74
	v_rcp_f32_e32 v76, v77
	s_nop 0
	v_mul_f32_e64 v87, v76, -v91
	v_mul_f32_e32 v76, -2.0, v87
	v_mul_f32_e32 v77, 0x3e4ccccd, v76
	v_fma_f32 v157, v76, s81, 1.0
	v_pk_mul_f32 v[78:79], v[76:77], v[156:157]
	v_mul_f32_e32 v102, 0x3eaaaaab, v76
	v_sub_f32_e32 v77, 1.0, v79
	v_fma_f32 v159, -v78, v77, 1.0
	v_mov_b32_e32 v77, v102
	v_pk_mul_f32 v[78:79], v[76:77], v[158:159]
	s_nop 0
	v_sub_f32_e32 v77, 1.0, v79
	v_fma_f32 v77, -v78, v77, 1.0
	v_mul_f32_e32 v76, v76, v77
	v_max_f32_e32 v76, 0, v76
	v_rcp_f32_e32 v75, v75
	v_sqrt_f32_e32 v76, v76
	s_nop 0
	v_mul_f32_e32 v75, v75, v76
	v_mul_f32_e32 v75, v75, v105
	v_cvt_pk_bf16_f32 v75, v87, v75
	v_lshl_add_u64 v[76:77], v[82:83], 2, s[36:37]
	global_store_dwordx4 v[76:77], v[72:75], off
	s_nop 1
	v_lshl_add_u64 v[76:77], v[166:167], 0, s[48:49]
	s_nop 0
	v_lshl_add_u64 v[72:73], v[76:77], 0, v[160:161]
	v_lshl_add_u64 v[74:75], v[72:73], 1, s[16:17]
	v_add_f32_e32 v68, v68, v96
	v_add_f32_e32 v69, v69, v97
	v_mul_f32_e32 v68, 0xbfb8aa3b, v68
	v_mul_f32_e32 v69, 0xbfb8aa3b, v69
	v_exp_f32_e32 v68, v68
	v_exp_f32_e32 v69, v69
	v_add_f32_e32 v64, v64, v92
	v_mul_f32_e32 v64, 0xbfb8aa3b, v64
	v_add_f32_e32 v68, 1.0, v68
	v_add_f32_e32 v82, 1.0, v69
	v_exp_f32_e32 v64, v64
	s_nop 0
	v_add_f32_e32 v64, 1.0, v64
	v_rcp_f32_e32 v68, v68
	s_nop 0
	v_mul_f32_e64 v84, v68, -v88
	v_mul_f32_e32 v68, -2.0, v84
	v_mul_f32_e32 v69, 0x3e4ccccd, v68
	v_fma_f32 v157, v68, s81, 1.0
	v_pk_mul_f32 v[78:79], v[68:69], v[156:157]
	v_mul_f32_e32 v88, 0x3eaaaaab, v68
	v_sub_f32_e32 v79, 1.0, v79
	v_mov_b32_e32 v69, v88
	v_fma_f32 v159, -v78, v79, 1.0
	v_pk_mul_f32 v[78:79], v[68:69], v[158:159]
	v_sub_f32_e32 v69, 1.0, v79
	v_fma_f32 v69, -v78, v69, 1.0
	v_mul_f32_e32 v68, v68, v69
	v_max_f32_e32 v68, 0, v68
	v_rcp_f32_e32 v64, v64
	v_add_f32_e32 v65, v65, v93
	v_mul_f32_e32 v65, 0xbfb8aa3b, v65
	v_exp_f32_e32 v65, v65
	s_nop 0
	v_add_f32_e32 v65, 1.0, v65
	v_add_f32_e32 v70, v70, v98
	v_mul_f32_e32 v70, 0xbfb8aa3b, v70
	v_exp_f32_e32 v70, v70
	s_waitcnt vmcnt(15) lgkmcnt(0)
; DI unsigned pk2(float a, float b) { f32x2 v = {a, b}; bf16v2_t r = __builtin_convertvector(v, bf16v2_t); return __builtin_bit_cast(unsigned, r); }
; DI float sigm(float x) { return 1.f / (1.f + __expf(-x)); }
;     DI void operator()(const Acc& acc, const Unit& u, int wr, int wc, int fr, int fq, const float (&pre)[8]) const {
;     ...
;             const f32x4 br = *(const f32x4*)(brg + f0 + 4 * n), bi = *(const f32x4*)(big + f0 + 4 * n), sp = *(const f32x4*)(sp8t + f0 + 4 * n);
; #pragma unroll
;             for (int ai = 0; ai < 2; ++ai)
; #pragma unroll
;                 for (int m = 0; m < 4; ++m) { const size_t o = (size_t)(row0 + ai * HALF + m * 16) * DM + f0 + 4 * n;
;                     const u32x2 xw = *(const u32x2*)(xc + o);
;                     const float xv[4] = {__uint_as_float(xw.x << 16), __uint_as_float(xw.x & 0xffff0000u), __uint_as_float(xw.y << 16), __uint_as_float(xw.y & 0xffff0000u)};
;                     u32x4 w;
; #pragma unroll
;                     for (int e = 0; e < 4; ++e) { const float r = sigm(acc[ai][0][m][n][e] + br[e]), ig = sigm(acc[ai][1][m][n][e] + bi[e]);
;                         const float la = -sp[e] * r, uu = -2.f * la;
;                         const float om = uu * (1.f - uu * 0.5f * (1.f - uu * (1.f / 3.f) * (1.f - uu * 0.25f * (1.f - uu * 0.2f * (1.f - uu * (1.f / 6.f))))));
;                         w[e] = pk2(la, sqrtf(fmaxf(om, 0.f)) * ig * xv[e]); }
;                     *(u32x4*)(ax + o) = w; __builtin_amdgcn_sched_barrier(0); }
	v_mov_b32_e32 v74, v208
	v_mov_b32_e32 v75, v209
	v_and_b32_e32 v78, 0xffff0000, v74
	v_lshlrev_b32_e32 v79, 16, v75
	v_sqrt_f32_e32 v68, v68
	s_nop 0
	v_mul_f32_e32 v64, v64, v68
	v_lshlrev_b32_e32 v68, 16, v74
	v_mul_f32_e32 v64, v64, v68
	v_rcp_f32_e32 v68, v82
	v_and_b32_e32 v85, 0xffff0000, v75
	v_mul_f32_e64 v86, v68, -v89
	v_mul_f32_e32 v68, -2.0, v86
	v_cvt_pk_bf16_f32 v64, v84, v64
	v_mul_f32_e32 v69, 0x3e4ccccd, v68
	v_fma_f32 v157, v68, s81, 1.0
	v_pk_mul_f32 v[74:75], v[68:69], v[156:157]
	v_mul_f32_e32 v87, 0x3eaaaaab, v68
	v_sub_f32_e32 v69, 1.0, v75
	v_fma_f32 v159, -v74, v69, 1.0
	v_mov_b32_e32 v69, v87
	v_pk_mul_f32 v[74:75], v[68:69], v[158:159]
	v_add_f32_e32 v66, v66, v94
	v_sub_f32_e32 v69, 1.0, v75
	v_fma_f32 v69, -v74, v69, 1.0
	v_mul_f32_e32 v68, v68, v69
	v_max_f32_e32 v68, 0, v68
	v_rcp_f32_e32 v65, v65
	v_mul_f32_e32 v66, 0xbfb8aa3b, v66
	v_exp_f32_e32 v66, v66
	v_add_f32_e32 v71, v71, v99
	v_add_f32_e32 v66, 1.0, v66
	v_mul_f32_e32 v71, 0xbfb8aa3b, v71
	v_exp_f32_e32 v71, v71
	v_add_f32_e32 v67, v67, v95
	v_mul_f32_e32 v67, 0xbfb8aa3b, v67
	v_sqrt_f32_e32 v68, v68
	v_add_f32_e32 v69, 1.0, v70
	v_mul_f32_e32 v65, v65, v68
	v_mul_f32_e32 v65, v65, v78
	v_exp_f32_e32 v67, v67
	v_rcp_f32_e32 v68, v69
	s_nop 0
	v_mul_f32_e64 v83, v68, -v90
	v_mul_f32_e32 v68, -2.0, v83
	v_mul_f32_e32 v69, 0x3e4ccccd, v68
	v_fma_f32 v157, v68, s81, 1.0
	v_pk_mul_f32 v[74:75], v[68:69], v[156:157]
	v_mul_f32_e32 v84, 0x3eaaaaab, v68
	v_sub_f32_e32 v69, 1.0, v75
	v_fma_f32 v159, -v74, v69, 1.0
	v_mov_b32_e32 v69, v84
	v_pk_mul_f32 v[74:75], v[68:69], v[158:159]
	v_sub_f32_e32 v69, 1.0, v75
	v_fma_f32 v69, -v74, v69, 1.0
	v_mul_f32_e32 v68, v68, v69
	v_max_f32_e32 v68, 0, v68
	v_rcp_f32_e32 v66, v66
	v_add_f32_e32 v67, 1.0, v67
	v_cvt_pk_bf16_f32 v65, v86, v65
	v_sqrt_f32_e32 v68, v68
	v_add_f32_e32 v69, 1.0, v71
	v_mul_f32_e32 v66, v66, v68
	v_mul_f32_e32 v66, v66, v79
	v_cvt_pk_bf16_f32 v66, v83, v66
	v_rcp_f32_e32 v68, v69
	s_nop 0
	v_mul_f32_e64 v79, v68, -v91
	v_mul_f32_e32 v68, -2.0, v79
	v_mul_f32_e32 v69, 0x3e4ccccd, v68
	v_fma_f32 v157, v68, s81, 1.0
	v_pk_mul_f32 v[70:71], v[68:69], v[156:157]
	v_mul_f32_e32 v82, 0x3eaaaaab, v68
	v_sub_f32_e32 v69, 1.0, v71
	v_fma_f32 v159, -v70, v69, 1.0
	v_mov_b32_e32 v69, v82
	v_pk_mul_f32 v[70:71], v[68:69], v[158:159]
	s_nop 0
	v_sub_f32_e32 v69, 1.0, v71
	v_fma_f32 v69, -v70, v69, 1.0
	v_mul_f32_e32 v68, v68, v69
	v_max_f32_e32 v68, 0, v68
	v_rcp_f32_e32 v67, v67
	v_sqrt_f32_e32 v68, v68
	s_nop 0
	v_mul_f32_e32 v67, v67, v68
	v_mul_f32_e32 v67, v67, v85
	v_cvt_pk_bf16_f32 v67, v79, v67
	v_lshl_add_u64 v[68:69], v[72:73], 2, s[36:37]
	global_store_dwordx4 v[68:69], v[64:67], off
	s_nop 0
	v_or_b32_e32 v160, 4, v160
	v_lshl_add_u64 v[78:79], v[166:167], 0, v[160:161]
	v_lshl_add_u64 v[64:65], v[78:79], 1, s[16:17]
	s_nop 0
	s_waitcnt vmcnt(15)
	v_mov_b32_e32 v82, v210
	v_mov_b32_e32 v83, v211
	v_mov_b32_e32 v72, v232
	v_mov_b32_e32 v73, v233
	v_mov_b32_e32 v74, v234
	v_mov_b32_e32 v75, v235
	v_mov_b32_e32 v68, v236
	v_mov_b32_e32 v69, v237
	v_mov_b32_e32 v70, v238
	v_mov_b32_e32 v71, v239
	v_mov_b32_e32 v64, v240
	v_mov_b32_e32 v65, v241
	v_mov_b32_e32 v66, v242
	v_mov_b32_e32 v67, v243
	v_add_f32_e32 v60, v60, v72
	v_add_f32_e32 v57, v57, v69
	v_mul_f32_e32 v60, 0xbfb8aa3b, v60
	v_add_f32_e32 v56, v56, v68
	v_mul_f32_e32 v57, 0xbfb8aa3b, v57
	v_exp_f32_e32 v60, v60
	v_add_f32_e32 v61, v61, v73
	v_mul_f32_e32 v56, 0xbfb8aa3b, v56
	v_exp_f32_e32 v57, v57
	v_mul_f32_e32 v61, 0xbfb8aa3b, v61
	v_exp_f32_e32 v56, v56
	v_exp_f32_e32 v61, v61
	v_add_f32_e32 v60, 1.0, v60
	v_add_f32_e32 v90, 1.0, v57
	v_add_f32_e32 v56, 1.0, v56
	s_waitcnt lgkmcnt(0)
	v_lshlrev_b32_e32 v88, 16, v83
	v_and_b32_e32 v89, 0xffff0000, v83
	v_add_f32_e32 v61, 1.0, v61
	v_lshlrev_b32_e32 v86, 16, v82
	v_and_b32_e32 v87, 0xffff0000, v82
	v_rcp_f32_e32 v57, v60
	s_nop 0
	v_mul_f32_e64 v93, v57, -v64
	v_rcp_f32_e32 v92, v56
	v_mul_f32_e32 v56, -2.0, v93
	v_rcp_f32_e32 v60, v61
	v_mul_f32_e32 v57, 0x3e4ccccd, v56
	v_fma_f32 v157, v56, s81, 1.0
	v_mul_f32_e32 v82, 0x3eaaaaab, v56
	v_mul_f32_e64 v94, v60, -v65
	v_pk_mul_f32 v[60:61], v[56:57], v[156:157]
	v_mov_b32_e32 v57, v82
	v_mul_f32_e32 v82, -2.0, v94
	v_sub_f32_e32 v61, 1.0, v61
	v_mul_f32_e32 v84, 0x3eaaaaab, v82
	v_mul_f32_e32 v83, 0x3e4ccccd, v82
	v_fma_f32 v157, v82, s81, 1.0
	v_fma_f32 v159, -v60, v61, 1.0
	v_pk_mul_f32 v[60:61], v[82:83], v[156:157]
	v_mov_b32_e32 v83, v84
	v_pk_mul_f32 v[84:85], v[56:57], v[158:159]
	v_sub_f32_e32 v57, 1.0, v61
	v_sub_f32_e32 v61, 1.0, v85
	v_fma_f32 v159, -v60, v57, 1.0
	v_fma_f32 v57, -v84, v61, 1.0
	v_mul_f32_e32 v56, v56, v57
	v_pk_mul_f32 v[60:61], v[82:83], v[158:159]
	v_max_f32_e32 v56, 0, v56
	v_sub_f32_e32 v57, 1.0, v61
	v_mul_f32_e32 v61, 0x4f800000, v56
	v_cmp_gt_f32_e32 vcc, s82, v56
	v_fma_f32 v57, -v60, v57, 1.0
	v_mul_f32_e32 v57, v82, v57
	v_cndmask_b32_e32 v56, v56, v61, vcc
	v_sqrt_f32_e32 v61, v56
	v_max_f32_e32 v57, 0, v57
	v_add_f32_e32 v62, v62, v74
	v_mul_f32_e32 v62, 0xbfb8aa3b, v62
	v_add_u32_e32 v60, -1, v61
	v_add_u32_e32 v82, 1, v61
	v_fma_f32 v83, -v60, v61, v56
	v_fma_f32 v84, -v82, v61, v56
	v_cmp_ge_f32_e64 s[12:13], 0, v83
	v_exp_f32_e32 v62, v62
	v_add_f32_e32 v58, v58, v70
	v_cndmask_b32_e64 v60, v61, v60, s[12:13]
	v_cmp_lt_f32_e64 s[12:13], 0, v84
	v_mul_f32_e32 v58, 0xbfb8aa3b, v58
	v_exp_f32_e32 v58, v58
	v_cndmask_b32_e64 v60, v60, v82, s[12:13]
	v_mul_f32_e32 v61, 0x37800000, v60
	v_cndmask_b32_e32 v60, v60, v61, vcc
	v_cmp_class_f32_e32 vcc, v56, v182
	v_add_f32_e32 v58, 1.0, v58
	s_nop 0
	v_cndmask_b32_e32 v56, v60, v56, vcc
	v_rcp_f32_e32 v61, v90
	v_mul_f32_e32 v56, v92, v56
; DI unsigned pk2(float a, float b) { f32x2 v = {a, b}; bf16v2_t r = __builtin_convertvector(v, bf16v2_t); return __builtin_bit_cast(unsigned, r); }
; DI float sigm(float x) { return 1.f / (1.f + __expf(-x)); }
;     DI void operator()(const Acc& acc, const Unit& u, int wr, int wc, int fr, int fq, const float (&pre)[8]) const {
;     ...
;                 for (int m = 0; m < 4; ++m) { const size_t o = (size_t)(row0 + ai * HALF + m * 16) * DM + f0 + 4 * n;
;                     const u32x2 xw = *(const u32x2*)(xc + o);
;                     const float xv[4] = {__uint_as_float(xw.x << 16), __uint_as_float(xw.x & 0xffff0000u), __uint_as_float(xw.y << 16), __uint_as_float(xw.y & 0xffff0000u)};
;                     u32x4 w;
; #pragma unroll
;                     for (int e = 0; e < 4; ++e) { const float r = sigm(acc[ai][0][m][n][e] + br[e]), ig = sigm(acc[ai][1][m][n][e] + bi[e]);
;                         const float la = -sp[e] * r, uu = -2.f * la;
;                         const float om = uu * (1.f - uu * 0.5f * (1.f - uu * (1.f / 3.f) * (1.f - uu * 0.25f * (1.f - uu * 0.2f * (1.f - uu * (1.f / 6.f))))));
;                         w[e] = pk2(la, sqrtf(fmaxf(om, 0.f)) * ig * xv[e]); }
;                     *(u32x4*)(ax + o) = w; __builtin_amdgcn_sched_barrier(0); }
	v_mul_f32_e32 v56, v56, v86
	v_add_f32_e32 v63, v63, v75
	v_mul_f32_e32 v63, 0xbfb8aa3b, v63
	v_exp_f32_e32 v63, v63
	v_sqrt_f32_e32 v57, v57
	v_add_f32_e32 v60, 1.0, v62
	v_mul_f32_e32 v57, v61, v57
	v_mul_f32_e32 v57, v57, v87
	v_add_f32_e32 v59, v59, v71
	v_rcp_f32_e32 v60, v60
	s_nop 0
	v_mul_f32_e64 v86, v60, -v66
	v_mul_f32_e32 v60, -2.0, v86
	v_mul_f32_e32 v61, 0x3e4ccccd, v60
	v_fma_f32 v157, v60, s81, 1.0
	v_pk_mul_f32 v[82:83], v[60:61], v[156:157]
	v_mul_f32_e32 v87, 0x3eaaaaab, v60
	v_sub_f32_e32 v61, 1.0, v83
	v_fma_f32 v159, -v82, v61, 1.0
	v_mov_b32_e32 v61, v87
	v_pk_mul_f32 v[82:83], v[60:61], v[158:159]
	v_sub_f32_e32 v61, 1.0, v83
	v_fma_f32 v61, -v82, v61, 1.0
	v_mul_f32_e32 v60, v60, v61
	v_max_f32_e32 v60, 0, v60
	v_rcp_f32_e32 v58, v58
	v_mul_f32_e32 v59, 0xbfb8aa3b, v59
	v_exp_f32_e32 v59, v59
	v_cvt_pk_bf16_f32 v56, v93, v56
	v_cvt_pk_bf16_f32 v57, v94, v57
	v_add_f32_e32 v59, 1.0, v59
	v_sqrt_f32_e32 v60, v60
	v_add_f32_e32 v61, 1.0, v63
	v_mul_f32_e32 v58, v58, v60
	v_mul_f32_e32 v58, v58, v88
	v_cvt_pk_bf16_f32 v58, v86, v58
	v_rcp_f32_e32 v60, v61
	s_nop 0
	v_mul_f32_e64 v85, v60, -v67
	v_mul_f32_e32 v60, -2.0, v85
	v_mul_f32_e32 v61, 0x3e4ccccd, v60
	v_fma_f32 v157, v60, s81, 1.0
	v_pk_mul_f32 v[62:63], v[60:61], v[156:157]
	v_mul_f32_e32 v86, 0x3eaaaaab, v60
	v_sub_f32_e32 v61, 1.0, v63
	v_fma_f32 v159, -v62, v61, 1.0
	v_mov_b32_e32 v61, v86
	v_pk_mul_f32 v[62:63], v[60:61], v[158:159]
	s_nop 0
	v_sub_f32_e32 v61, 1.0, v63
	v_fma_f32 v61, -v62, v61, 1.0
	v_mul_f32_e32 v60, v60, v61
	v_max_f32_e32 v60, 0, v60
	v_rcp_f32_e32 v59, v59
	v_sqrt_f32_e32 v60, v60
	s_nop 0
	v_mul_f32_e32 v59, v59, v60
	v_mul_f32_e32 v59, v59, v89
	v_cvt_pk_bf16_f32 v59, v85, v59
	v_lshl_add_u64 v[60:61], v[78:79], 2, s[36:37]
	global_store_dwordx4 v[60:61], v[56:59], off
	s_nop 1
	v_lshl_add_u64 v[56:57], v[132:133], 0, v[160:161]
	v_lshl_add_u64 v[58:59], v[56:57], 1, s[16:17]
	v_add_f32_e32 v52, v52, v72
	v_add_f32_e32 v53, v53, v73
	v_mul_f32_e32 v52, 0xbfb8aa3b, v52
	v_mul_f32_e32 v53, 0xbfb8aa3b, v53
	v_exp_f32_e32 v52, v52
	v_exp_f32_e32 v53, v53
	v_add_f32_e32 v48, v48, v68
	v_mul_f32_e32 v48, 0xbfb8aa3b, v48
	v_add_f32_e32 v52, 1.0, v52
	v_add_f32_e32 v62, 1.0, v53
	v_exp_f32_e32 v48, v48
	s_nop 0
	v_add_f32_e32 v48, 1.0, v48
	v_rcp_f32_e32 v52, v52
	s_nop 0
	v_mul_f32_e64 v78, v52, -v64
	v_mul_f32_e32 v52, -2.0, v78
	v_mul_f32_e32 v53, 0x3e4ccccd, v52
	v_fma_f32 v157, v52, s81, 1.0
	v_pk_mul_f32 v[60:61], v[52:53], v[156:157]
	v_mul_f32_e32 v84, 0x3eaaaaab, v52
	v_sub_f32_e32 v61, 1.0, v61
	v_mov_b32_e32 v53, v84
	v_fma_f32 v159, -v60, v61, 1.0
	v_pk_mul_f32 v[60:61], v[52:53], v[158:159]
	v_sub_f32_e32 v53, 1.0, v61
	v_fma_f32 v53, -v60, v53, 1.0
	v_mul_f32_e32 v52, v52, v53
	v_max_f32_e32 v52, 0, v52
	v_rcp_f32_e32 v48, v48
	v_add_f32_e32 v49, v49, v69
	v_mul_f32_e32 v49, 0xbfb8aa3b, v49
	v_exp_f32_e32 v49, v49
	s_nop 0
	v_add_f32_e32 v49, 1.0, v49
	v_add_f32_e32 v54, v54, v74
	v_mul_f32_e32 v54, 0xbfb8aa3b, v54
	v_exp_f32_e32 v54, v54
	s_waitcnt vmcnt(15) lgkmcnt(0)
	v_mov_b32_e32 v58, v212
	v_mov_b32_e32 v59, v213
	v_and_b32_e32 v60, 0xffff0000, v58
	v_lshlrev_b32_e32 v61, 16, v59
	v_sqrt_f32_e32 v52, v52
	s_nop 0
	v_mul_f32_e32 v48, v48, v52
	v_lshlrev_b32_e32 v52, 16, v58
	v_mul_f32_e32 v48, v48, v52
	v_rcp_f32_e32 v52, v62
	v_and_b32_e32 v79, 0xffff0000, v59
	v_mul_f32_e64 v82, v52, -v65
	v_mul_f32_e32 v52, -2.0, v82
	v_cvt_pk_bf16_f32 v48, v78, v48
	v_mul_f32_e32 v53, 0x3e4ccccd, v52
	v_fma_f32 v157, v52, s81, 1.0
	v_pk_mul_f32 v[58:59], v[52:53], v[156:157]
	v_mul_f32_e32 v83, 0x3eaaaaab, v52
	v_sub_f32_e32 v53, 1.0, v59
	v_fma_f32 v159, -v58, v53, 1.0
	v_mov_b32_e32 v53, v83
	v_pk_mul_f32 v[58:59], v[52:53], v[158:159]
	v_add_f32_e32 v50, v50, v70
	v_sub_f32_e32 v53, 1.0, v59
	v_fma_f32 v53, -v58, v53, 1.0
	v_mul_f32_e32 v52, v52, v53
	v_max_f32_e32 v52, 0, v52
	v_rcp_f32_e32 v49, v49
	v_mul_f32_e32 v50, 0xbfb8aa3b, v50
	v_exp_f32_e32 v50, v50
	v_add_f32_e32 v55, v55, v75
	v_add_f32_e32 v50, 1.0, v50
	v_mul_f32_e32 v55, 0xbfb8aa3b, v55
	v_exp_f32_e32 v55, v55
	v_add_f32_e32 v51, v51, v71
	v_mul_f32_e32 v51, 0xbfb8aa3b, v51
	v_sqrt_f32_e32 v52, v52
	v_add_f32_e32 v53, 1.0, v54
	v_mul_f32_e32 v49, v49, v52
	v_mul_f32_e32 v49, v49, v60
	v_exp_f32_e32 v51, v51
	v_rcp_f32_e32 v52, v53
	s_nop 0
	v_mul_f32_e64 v63, v52, -v66
	v_mul_f32_e32 v52, -2.0, v63
	v_mul_f32_e32 v53, 0x3e4ccccd, v52
	v_fma_f32 v157, v52, s81, 1.0
	v_pk_mul_f32 v[58:59], v[52:53], v[156:157]
	v_mul_f32_e32 v78, 0x3eaaaaab, v52
	v_sub_f32_e32 v53, 1.0, v59
	v_fma_f32 v159, -v58, v53, 1.0
	v_mov_b32_e32 v53, v78
	v_pk_mul_f32 v[58:59], v[52:53], v[158:159]
	v_sub_f32_e32 v53, 1.0, v59
	v_fma_f32 v53, -v58, v53, 1.0
	v_mul_f32_e32 v52, v52, v53
	v_max_f32_e32 v52, 0, v52
	v_rcp_f32_e32 v50, v50
	v_add_f32_e32 v51, 1.0, v51
	v_cvt_pk_bf16_f32 v49, v82, v49
	v_sqrt_f32_e32 v52, v52
	v_add_f32_e32 v53, 1.0, v55
	v_mul_f32_e32 v50, v50, v52
	v_mul_f32_e32 v50, v50, v61
	v_cvt_pk_bf16_f32 v50, v63, v50
	v_rcp_f32_e32 v52, v53
	s_nop 0
	v_mul_f32_e64 v61, v52, -v67
	v_mul_f32_e32 v52, -2.0, v61
	v_mul_f32_e32 v53, 0x3e4ccccd, v52
	v_fma_f32 v157, v52, s81, 1.0
	v_pk_mul_f32 v[54:55], v[52:53], v[156:157]
	v_mul_f32_e32 v62, 0x3eaaaaab, v52
	v_sub_f32_e32 v53, 1.0, v55
	v_fma_f32 v159, -v54, v53, 1.0
	v_mov_b32_e32 v53, v62
	v_pk_mul_f32 v[54:55], v[52:53], v[158:159]
	s_nop 0
	v_sub_f32_e32 v53, 1.0, v55
	v_fma_f32 v53, -v54, v53, 1.0
	v_mul_f32_e32 v52, v52, v53
	v_max_f32_e32 v52, 0, v52
	v_rcp_f32_e32 v51, v51
	v_sqrt_f32_e32 v52, v52
	s_nop 0
	v_mul_f32_e32 v51, v51, v52
	v_mul_f32_e32 v51, v51, v79
	v_cvt_pk_bf16_f32 v51, v61, v51
	v_lshl_add_u64 v[52:53], v[56:57], 2, s[36:37]
	global_store_dwordx4 v[52:53], v[48:51], off
	s_nop 1
	v_lshl_add_u64 v[48:49], v[124:125], 0, v[160:161]
	v_lshl_add_u64 v[50:51], v[48:49], 1, s[16:17]
	v_add_f32_e32 v44, v44, v72
	v_add_f32_e32 v45, v45, v73
	v_mul_f32_e32 v44, 0xbfb8aa3b, v44
	v_mul_f32_e32 v45, 0xbfb8aa3b, v45
	v_exp_f32_e32 v44, v44
	v_exp_f32_e32 v45, v45
	v_add_f32_e32 v40, v40, v68
	v_mul_f32_e32 v40, 0xbfb8aa3b, v40
	v_add_f32_e32 v44, 1.0, v44
	v_add_f32_e32 v54, 1.0, v45
	v_exp_f32_e32 v40, v40
	s_nop 0
	v_add_f32_e32 v40, 1.0, v40
	v_rcp_f32_e32 v44, v44
	s_nop 0
	v_mul_f32_e64 v56, v44, -v64
	v_mul_f32_e32 v44, -2.0, v56
	v_mul_f32_e32 v45, 0x3e4ccccd, v44
	v_fma_f32 v157, v44, s81, 1.0
	v_pk_mul_f32 v[52:53], v[44:45], v[156:157]
	v_mul_f32_e32 v60, 0x3eaaaaab, v44
	v_sub_f32_e32 v53, 1.0, v53
	v_mov_b32_e32 v45, v60
	v_fma_f32 v159, -v52, v53, 1.0
	v_pk_mul_f32 v[52:53], v[44:45], v[158:159]
	v_sub_f32_e32 v45, 1.0, v53
	v_fma_f32 v45, -v52, v45, 1.0
	v_mul_f32_e32 v44, v44, v45
	v_max_f32_e32 v44, 0, v44
	v_rcp_f32_e32 v40, v40
	v_add_f32_e32 v41, v41, v69
	v_mul_f32_e32 v41, 0xbfb8aa3b, v41
	v_exp_f32_e32 v41, v41
	s_nop 0
	v_add_f32_e32 v41, 1.0, v41
	v_add_f32_e32 v46, v46, v74
	v_mul_f32_e32 v46, 0xbfb8aa3b, v46
	v_exp_f32_e32 v46, v46
	s_waitcnt vmcnt(15) lgkmcnt(0)
; DI unsigned pk2(float a, float b) { f32x2 v = {a, b}; bf16v2_t r = __builtin_convertvector(v, bf16v2_t); return __builtin_bit_cast(unsigned, r); }
; DI float sigm(float x) { return 1.f / (1.f + __expf(-x)); }
;     DI void operator()(const Acc& acc, const Unit& u, int wr, int wc, int fr, int fq, const float (&pre)[8]) const {
;     ...
;                 for (int m = 0; m < 4; ++m) { const size_t o = (size_t)(row0 + ai * HALF + m * 16) * DM + f0 + 4 * n;
;                     const u32x2 xw = *(const u32x2*)(xc + o);
;                     const float xv[4] = {__uint_as_float(xw.x << 16), __uint_as_float(xw.x & 0xffff0000u), __uint_as_float(xw.y << 16), __uint_as_float(xw.y & 0xffff0000u)};
;                     u32x4 w;
; #pragma unroll
;                     for (int e = 0; e < 4; ++e) { const float r = sigm(acc[ai][0][m][n][e] + br[e]), ig = sigm(acc[ai][1][m][n][e] + bi[e]);
;                         const float la = -sp[e] * r, uu = -2.f * la;
;                         const float om = uu * (1.f - uu * 0.5f * (1.f - uu * (1.f / 3.f) * (1.f - uu * 0.25f * (1.f - uu * 0.2f * (1.f - uu * (1.f / 6.f))))));
;                         w[e] = pk2(la, sqrtf(fmaxf(om, 0.f)) * ig * xv[e]); }
;                     *(u32x4*)(ax + o) = w; __builtin_amdgcn_sched_barrier(0); }
	v_mov_b32_e32 v50, v214
	v_mov_b32_e32 v51, v215
	v_and_b32_e32 v52, 0xffff0000, v50
	v_lshlrev_b32_e32 v53, 16, v51
	v_sqrt_f32_e32 v44, v44
	s_nop 0
	v_mul_f32_e32 v40, v40, v44
	v_lshlrev_b32_e32 v44, 16, v50
	v_mul_f32_e32 v40, v40, v44
	v_rcp_f32_e32 v44, v54
	v_and_b32_e32 v57, 0xffff0000, v51
	v_mul_f32_e64 v58, v44, -v65
	v_mul_f32_e32 v44, -2.0, v58
	v_cvt_pk_bf16_f32 v40, v56, v40
	v_mul_f32_e32 v45, 0x3e4ccccd, v44
	v_fma_f32 v157, v44, s81, 1.0
	v_pk_mul_f32 v[50:51], v[44:45], v[156:157]
	v_mul_f32_e32 v59, 0x3eaaaaab, v44
	v_sub_f32_e32 v45, 1.0, v51
	v_fma_f32 v159, -v50, v45, 1.0
	v_mov_b32_e32 v45, v59
	v_pk_mul_f32 v[50:51], v[44:45], v[158:159]
	v_add_f32_e32 v42, v42, v70
	v_sub_f32_e32 v45, 1.0, v51
	v_fma_f32 v45, -v50, v45, 1.0
	v_mul_f32_e32 v44, v44, v45
	v_max_f32_e32 v44, 0, v44
	v_rcp_f32_e32 v41, v41
	v_mul_f32_e32 v42, 0xbfb8aa3b, v42
	v_exp_f32_e32 v42, v42
	v_add_f32_e32 v47, v47, v75
	v_add_f32_e32 v42, 1.0, v42
	v_mul_f32_e32 v47, 0xbfb8aa3b, v47
	v_exp_f32_e32 v47, v47
	v_add_f32_e32 v43, v43, v71
	v_mul_f32_e32 v43, 0xbfb8aa3b, v43
	v_sqrt_f32_e32 v44, v44
	v_add_f32_e32 v45, 1.0, v46
	v_mul_f32_e32 v41, v41, v44
	v_mul_f32_e32 v41, v41, v52
	v_exp_f32_e32 v43, v43
	v_rcp_f32_e32 v44, v45
	s_nop 0
	v_mul_f32_e64 v55, v44, -v66
	v_mul_f32_e32 v44, -2.0, v55
	v_mul_f32_e32 v45, 0x3e4ccccd, v44
	v_fma_f32 v157, v44, s81, 1.0
	v_pk_mul_f32 v[50:51], v[44:45], v[156:157]
	v_mul_f32_e32 v56, 0x3eaaaaab, v44
	v_sub_f32_e32 v45, 1.0, v51
	v_fma_f32 v159, -v50, v45, 1.0
	v_mov_b32_e32 v45, v56
	v_pk_mul_f32 v[50:51], v[44:45], v[158:159]
	v_sub_f32_e32 v45, 1.0, v51
	v_fma_f32 v45, -v50, v45, 1.0
	v_mul_f32_e32 v44, v44, v45
	v_max_f32_e32 v44, 0, v44
	v_rcp_f32_e32 v42, v42
	v_add_f32_e32 v43, 1.0, v43
	v_cvt_pk_bf16_f32 v41, v58, v41
	v_sqrt_f32_e32 v44, v44
	v_add_f32_e32 v45, 1.0, v47
	v_mul_f32_e32 v42, v42, v44
	v_mul_f32_e32 v42, v42, v53
	v_cvt_pk_bf16_f32 v42, v55, v42
	v_rcp_f32_e32 v44, v45
	s_nop 0
	v_mul_f32_e64 v53, v44, -v67
	v_mul_f32_e32 v44, -2.0, v53
	v_mul_f32_e32 v45, 0x3e4ccccd, v44
	v_fma_f32 v157, v44, s81, 1.0
	v_pk_mul_f32 v[46:47], v[44:45], v[156:157]
	v_mul_f32_e32 v54, 0x3eaaaaab, v44
	v_sub_f32_e32 v45, 1.0, v47
	v_fma_f32 v159, -v46, v45, 1.0
	v_mov_b32_e32 v45, v54
	v_pk_mul_f32 v[46:47], v[44:45], v[158:159]
	s_nop 0
	v_sub_f32_e32 v45, 1.0, v47
	v_fma_f32 v45, -v46, v45, 1.0
	v_mul_f32_e32 v44, v44, v45
	v_max_f32_e32 v44, 0, v44
	v_rcp_f32_e32 v43, v43
	v_sqrt_f32_e32 v44, v44
	s_nop 0
	v_mul_f32_e32 v43, v43, v44
	v_mul_f32_e32 v43, v43, v57
	v_cvt_pk_bf16_f32 v43, v53, v43
	v_lshl_add_u64 v[44:45], v[48:49], 2, s[36:37]
	global_store_dwordx4 v[44:45], v[40:43], off
	s_nop 1
	v_lshl_add_u64 v[40:41], v[116:117], 0, v[160:161]
	v_lshl_add_u64 v[42:43], v[40:41], 1, s[16:17]
	v_add_f32_e32 v36, v36, v72
	v_add_f32_e32 v37, v37, v73
	v_mul_f32_e32 v36, 0xbfb8aa3b, v36
	v_mul_f32_e32 v37, 0xbfb8aa3b, v37
	v_exp_f32_e32 v36, v36
	v_exp_f32_e32 v37, v37
	v_add_f32_e32 v32, v32, v68
	v_mul_f32_e32 v32, 0xbfb8aa3b, v32
	v_add_f32_e32 v36, 1.0, v36
	v_add_f32_e32 v46, 1.0, v37
	v_exp_f32_e32 v32, v32
	s_nop 0
	v_add_f32_e32 v32, 1.0, v32
	v_rcp_f32_e32 v36, v36
	s_nop 0
	v_mul_f32_e64 v48, v36, -v64
	v_mul_f32_e32 v36, -2.0, v48
	v_mul_f32_e32 v37, 0x3e4ccccd, v36
	v_fma_f32 v157, v36, s81, 1.0
	v_pk_mul_f32 v[44:45], v[36:37], v[156:157]
	v_mul_f32_e32 v52, 0x3eaaaaab, v36
	v_sub_f32_e32 v45, 1.0, v45
	v_mov_b32_e32 v37, v52
	v_fma_f32 v159, -v44, v45, 1.0
	v_pk_mul_f32 v[44:45], v[36:37], v[158:159]
	v_sub_f32_e32 v37, 1.0, v45
	v_fma_f32 v37, -v44, v37, 1.0
	v_mul_f32_e32 v36, v36, v37
	v_max_f32_e32 v36, 0, v36
	v_rcp_f32_e32 v32, v32
	v_add_f32_e32 v33, v33, v69
	v_mul_f32_e32 v33, 0xbfb8aa3b, v33
	v_exp_f32_e32 v33, v33
	s_nop 0
	v_add_f32_e32 v33, 1.0, v33
	v_add_f32_e32 v38, v38, v74
	v_mul_f32_e32 v38, 0xbfb8aa3b, v38
	v_exp_f32_e32 v38, v38
	s_waitcnt vmcnt(15) lgkmcnt(0)
	v_mov_b32_e32 v42, v216
	v_mov_b32_e32 v43, v217
	v_and_b32_e32 v44, 0xffff0000, v42
	v_lshlrev_b32_e32 v45, 16, v43
	v_sqrt_f32_e32 v36, v36
	s_nop 0
	v_mul_f32_e32 v32, v32, v36
	v_lshlrev_b32_e32 v36, 16, v42
	v_mul_f32_e32 v32, v32, v36
	v_rcp_f32_e32 v36, v46
	v_and_b32_e32 v49, 0xffff0000, v43
	v_mul_f32_e64 v50, v36, -v65
	v_mul_f32_e32 v36, -2.0, v50
	v_cvt_pk_bf16_f32 v32, v48, v32
	v_mul_f32_e32 v37, 0x3e4ccccd, v36
	v_fma_f32 v157, v36, s81, 1.0
	v_pk_mul_f32 v[42:43], v[36:37], v[156:157]
	v_mul_f32_e32 v51, 0x3eaaaaab, v36
	v_sub_f32_e32 v37, 1.0, v43
	v_fma_f32 v159, -v42, v37, 1.0
	v_mov_b32_e32 v37, v51
	v_pk_mul_f32 v[42:43], v[36:37], v[158:159]
	v_add_f32_e32 v34, v34, v70
	v_sub_f32_e32 v37, 1.0, v43
	v_fma_f32 v37, -v42, v37, 1.0
	v_mul_f32_e32 v36, v36, v37
	v_max_f32_e32 v36, 0, v36
	v_rcp_f32_e32 v33, v33
	v_mul_f32_e32 v34, 0xbfb8aa3b, v34
	v_exp_f32_e32 v34, v34
	v_add_f32_e32 v39, v39, v75
	v_add_f32_e32 v34, 1.0, v34
	v_mul_f32_e32 v39, 0xbfb8aa3b, v39
	v_exp_f32_e32 v39, v39
	v_add_f32_e32 v35, v35, v71
	v_mul_f32_e32 v35, 0xbfb8aa3b, v35
	v_sqrt_f32_e32 v36, v36
	v_add_f32_e32 v37, 1.0, v38
	v_mul_f32_e32 v33, v33, v36
	v_mul_f32_e32 v33, v33, v44
	v_exp_f32_e32 v35, v35
	v_rcp_f32_e32 v36, v37
	s_nop 0
	v_mul_f32_e64 v47, v36, -v66
	v_mul_f32_e32 v36, -2.0, v47
	v_mul_f32_e32 v37, 0x3e4ccccd, v36
	v_fma_f32 v157, v36, s81, 1.0
	v_pk_mul_f32 v[42:43], v[36:37], v[156:157]
	v_mul_f32_e32 v48, 0x3eaaaaab, v36
	v_sub_f32_e32 v37, 1.0, v43
	v_fma_f32 v159, -v42, v37, 1.0
	v_mov_b32_e32 v37, v48
	v_pk_mul_f32 v[42:43], v[36:37], v[158:159]
	v_sub_f32_e32 v37, 1.0, v43
	v_fma_f32 v37, -v42, v37, 1.0
	v_mul_f32_e32 v36, v36, v37
	v_max_f32_e32 v36, 0, v36
	v_rcp_f32_e32 v34, v34
; DI unsigned pk2(float a, float b) { f32x2 v = {a, b}; bf16v2_t r = __builtin_convertvector(v, bf16v2_t); return __builtin_bit_cast(unsigned, r); }
; DI float sigm(float x) { return 1.f / (1.f + __expf(-x)); }
;     DI void operator()(const Acc& acc, const Unit& u, int wr, int wc, int fr, int fq, const float (&pre)[8]) const {
;     ...
;                 for (int m = 0; m < 4; ++m) { const size_t o = (size_t)(row0 + ai * HALF + m * 16) * DM + f0 + 4 * n;
;                     const u32x2 xw = *(const u32x2*)(xc + o);
;                     const float xv[4] = {__uint_as_float(xw.x << 16), __uint_as_float(xw.x & 0xffff0000u), __uint_as_float(xw.y << 16), __uint_as_float(xw.y & 0xffff0000u)};
;                     u32x4 w;
; #pragma unroll
;                     for (int e = 0; e < 4; ++e) { const float r = sigm(acc[ai][0][m][n][e] + br[e]), ig = sigm(acc[ai][1][m][n][e] + bi[e]);
;                         const float la = -sp[e] * r, uu = -2.f * la;
;                         const float om = uu * (1.f - uu * 0.5f * (1.f - uu * (1.f / 3.f) * (1.f - uu * 0.25f * (1.f - uu * 0.2f * (1.f - uu * (1.f / 6.f))))));
;                         w[e] = pk2(la, sqrtf(fmaxf(om, 0.f)) * ig * xv[e]); }
;                     *(u32x4*)(ax + o) = w; __builtin_amdgcn_sched_barrier(0); }
	v_add_f32_e32 v35, 1.0, v35
	v_cvt_pk_bf16_f32 v33, v50, v33
	v_sqrt_f32_e32 v36, v36
	v_add_f32_e32 v37, 1.0, v39
	v_mul_f32_e32 v34, v34, v36
	v_mul_f32_e32 v34, v34, v45
	v_cvt_pk_bf16_f32 v34, v47, v34
	v_rcp_f32_e32 v36, v37
	s_nop 0
	v_mul_f32_e64 v45, v36, -v67
	v_mul_f32_e32 v36, -2.0, v45
	v_mul_f32_e32 v37, 0x3e4ccccd, v36
	v_fma_f32 v157, v36, s81, 1.0
	v_pk_mul_f32 v[38:39], v[36:37], v[156:157]
	v_mul_f32_e32 v46, 0x3eaaaaab, v36
	v_sub_f32_e32 v37, 1.0, v39
	v_fma_f32 v159, -v38, v37, 1.0
	v_mov_b32_e32 v37, v46
	v_pk_mul_f32 v[38:39], v[36:37], v[158:159]
	s_nop 0
	v_sub_f32_e32 v37, 1.0, v39
	v_fma_f32 v37, -v38, v37, 1.0
	v_mul_f32_e32 v36, v36, v37
	v_max_f32_e32 v36, 0, v36
	v_rcp_f32_e32 v35, v35
	v_sqrt_f32_e32 v36, v36
	s_nop 0
	v_mul_f32_e32 v35, v35, v36
	v_mul_f32_e32 v35, v35, v49
	v_cvt_pk_bf16_f32 v35, v45, v35
	v_lshl_add_u64 v[36:37], v[40:41], 2, s[36:37]
	global_store_dwordx4 v[36:37], v[32:35], off
	s_nop 1
	v_lshl_add_u64 v[32:33], v[108:109], 0, v[160:161]
	v_lshl_add_u64 v[34:35], v[32:33], 1, s[16:17]
	v_add_f32_e32 v28, v28, v72
	v_add_f32_e32 v29, v29, v73
	v_mul_f32_e32 v28, 0xbfb8aa3b, v28
	v_mul_f32_e32 v29, 0xbfb8aa3b, v29
	v_exp_f32_e32 v28, v28
	v_exp_f32_e32 v29, v29
	v_add_f32_e32 v24, v24, v68
	v_mul_f32_e32 v24, 0xbfb8aa3b, v24
	v_add_f32_e32 v28, 1.0, v28
	v_add_f32_e32 v38, 1.0, v29
	v_exp_f32_e32 v24, v24
	s_nop 0
	v_add_f32_e32 v24, 1.0, v24
	v_rcp_f32_e32 v28, v28
	s_nop 0
	v_mul_f32_e64 v40, v28, -v64
	v_mul_f32_e32 v28, -2.0, v40
	v_mul_f32_e32 v29, 0x3e4ccccd, v28
	v_fma_f32 v157, v28, s81, 1.0
	v_pk_mul_f32 v[36:37], v[28:29], v[156:157]
	v_mul_f32_e32 v44, 0x3eaaaaab, v28
	v_sub_f32_e32 v37, 1.0, v37
	v_mov_b32_e32 v29, v44
	v_fma_f32 v159, -v36, v37, 1.0
	v_pk_mul_f32 v[36:37], v[28:29], v[158:159]
	v_sub_f32_e32 v29, 1.0, v37
	v_fma_f32 v29, -v36, v29, 1.0
	v_mul_f32_e32 v28, v28, v29
	v_max_f32_e32 v28, 0, v28
	v_rcp_f32_e32 v24, v24
	v_add_f32_e32 v25, v25, v69
	v_mul_f32_e32 v25, 0xbfb8aa3b, v25
	v_exp_f32_e32 v25, v25
	s_nop 0
	v_add_f32_e32 v25, 1.0, v25
	v_add_f32_e32 v30, v30, v74
	v_mul_f32_e32 v30, 0xbfb8aa3b, v30
	v_exp_f32_e32 v30, v30
	s_waitcnt vmcnt(15) lgkmcnt(0)
	v_mov_b32_e32 v34, v218
	v_mov_b32_e32 v35, v219
	v_and_b32_e32 v36, 0xffff0000, v34
	v_lshlrev_b32_e32 v37, 16, v35
	v_sqrt_f32_e32 v28, v28
	s_nop 0
	v_mul_f32_e32 v24, v24, v28
	v_lshlrev_b32_e32 v28, 16, v34
	v_mul_f32_e32 v24, v24, v28
	v_rcp_f32_e32 v28, v38
	v_and_b32_e32 v41, 0xffff0000, v35
	v_mul_f32_e64 v42, v28, -v65
	v_mul_f32_e32 v28, -2.0, v42
	v_cvt_pk_bf16_f32 v24, v40, v24
	v_mul_f32_e32 v29, 0x3e4ccccd, v28
	v_fma_f32 v157, v28, s81, 1.0
	v_pk_mul_f32 v[34:35], v[28:29], v[156:157]
	v_mul_f32_e32 v43, 0x3eaaaaab, v28
	v_sub_f32_e32 v29, 1.0, v35
	v_fma_f32 v159, -v34, v29, 1.0
	v_mov_b32_e32 v29, v43
	v_pk_mul_f32 v[34:35], v[28:29], v[158:159]
	v_add_f32_e32 v26, v26, v70
	v_sub_f32_e32 v29, 1.0, v35
	v_fma_f32 v29, -v34, v29, 1.0
	v_mul_f32_e32 v28, v28, v29
	v_max_f32_e32 v28, 0, v28
	v_rcp_f32_e32 v25, v25
	v_mul_f32_e32 v26, 0xbfb8aa3b, v26
	v_exp_f32_e32 v26, v26
	v_add_f32_e32 v31, v31, v75
	v_add_f32_e32 v26, 1.0, v26
	v_mul_f32_e32 v31, 0xbfb8aa3b, v31
	v_exp_f32_e32 v31, v31
	v_add_f32_e32 v27, v27, v71
	v_mul_f32_e32 v27, 0xbfb8aa3b, v27
	v_sqrt_f32_e32 v28, v28
	v_add_f32_e32 v29, 1.0, v30
	v_mul_f32_e32 v25, v25, v28
	v_mul_f32_e32 v25, v25, v36
	v_exp_f32_e32 v27, v27
	v_rcp_f32_e32 v28, v29
	s_nop 0
	v_mul_f32_e64 v39, v28, -v66
	v_mul_f32_e32 v28, -2.0, v39
	v_mul_f32_e32 v29, 0x3e4ccccd, v28
	v_fma_f32 v157, v28, s81, 1.0
	v_pk_mul_f32 v[34:35], v[28:29], v[156:157]
	v_mul_f32_e32 v40, 0x3eaaaaab, v28
	v_sub_f32_e32 v29, 1.0, v35
	v_fma_f32 v159, -v34, v29, 1.0
	v_mov_b32_e32 v29, v40
	v_pk_mul_f32 v[34:35], v[28:29], v[158:159]
	v_sub_f32_e32 v29, 1.0, v35
	v_fma_f32 v29, -v34, v29, 1.0
	v_mul_f32_e32 v28, v28, v29
	v_max_f32_e32 v28, 0, v28
	v_rcp_f32_e32 v26, v26
	v_add_f32_e32 v27, 1.0, v27
	v_cvt_pk_bf16_f32 v25, v42, v25
	v_sqrt_f32_e32 v28, v28
	v_add_f32_e32 v29, 1.0, v31
	v_mul_f32_e32 v26, v26, v28
	v_mul_f32_e32 v26, v26, v37
	v_cvt_pk_bf16_f32 v26, v39, v26
	v_rcp_f32_e32 v28, v29
	s_nop 0
	v_mul_f32_e64 v37, v28, -v67
	v_mul_f32_e32 v28, -2.0, v37
	v_mul_f32_e32 v29, 0x3e4ccccd, v28
	v_fma_f32 v157, v28, s81, 1.0
	v_pk_mul_f32 v[30:31], v[28:29], v[156:157]
	v_mul_f32_e32 v38, 0x3eaaaaab, v28
	v_sub_f32_e32 v29, 1.0, v31
	v_fma_f32 v159, -v30, v29, 1.0
	v_mov_b32_e32 v29, v38
	v_pk_mul_f32 v[30:31], v[28:29], v[158:159]
	s_nop 0
	v_sub_f32_e32 v29, 1.0, v31
	v_fma_f32 v29, -v30, v29, 1.0
	v_mul_f32_e32 v28, v28, v29
	v_max_f32_e32 v28, 0, v28
	v_rcp_f32_e32 v27, v27
	v_sqrt_f32_e32 v28, v28
	s_nop 0
	v_mul_f32_e32 v27, v27, v28
	v_mul_f32_e32 v27, v27, v41
	v_cvt_pk_bf16_f32 v27, v37, v27
	v_lshl_add_u64 v[28:29], v[32:33], 2, s[36:37]
	global_store_dwordx4 v[28:29], v[24:27], off
	s_nop 1
	v_lshl_add_u64 v[24:25], v[100:101], 0, v[160:161]
	v_lshl_add_u64 v[26:27], v[24:25], 1, s[16:17]
	v_add_f32_e32 v20, v20, v72
	v_add_f32_e32 v21, v21, v73
	v_mul_f32_e32 v20, 0xbfb8aa3b, v20
	v_mul_f32_e32 v21, 0xbfb8aa3b, v21
	v_exp_f32_e32 v20, v20
	v_exp_f32_e32 v21, v21
	v_add_f32_e32 v16, v16, v68
	v_mul_f32_e32 v16, 0xbfb8aa3b, v16
	v_add_f32_e32 v20, 1.0, v20
	v_add_f32_e32 v30, 1.0, v21
	v_exp_f32_e32 v16, v16
	s_nop 0
	v_add_f32_e32 v16, 1.0, v16
	v_rcp_f32_e32 v20, v20
	s_nop 0
	v_mul_f32_e64 v32, v20, -v64
	v_mul_f32_e32 v20, -2.0, v32
	v_mul_f32_e32 v21, 0x3e4ccccd, v20
	v_fma_f32 v157, v20, s81, 1.0
	v_pk_mul_f32 v[28:29], v[20:21], v[156:157]
	v_mul_f32_e32 v36, 0x3eaaaaab, v20
	v_sub_f32_e32 v29, 1.0, v29
	v_mov_b32_e32 v21, v36
	v_fma_f32 v159, -v28, v29, 1.0
	v_pk_mul_f32 v[28:29], v[20:21], v[158:159]
	v_sub_f32_e32 v21, 1.0, v29
	v_fma_f32 v21, -v28, v21, 1.0
	v_mul_f32_e32 v20, v20, v21
	v_max_f32_e32 v20, 0, v20
	v_rcp_f32_e32 v16, v16
	v_add_f32_e32 v17, v17, v69
	v_mul_f32_e32 v17, 0xbfb8aa3b, v17
	v_exp_f32_e32 v17, v17
	s_nop 0
	v_add_f32_e32 v17, 1.0, v17
	v_add_f32_e32 v22, v22, v74
	v_mul_f32_e32 v22, 0xbfb8aa3b, v22
	v_exp_f32_e32 v22, v22
	s_waitcnt vmcnt(15) lgkmcnt(0)
; DI unsigned pk2(float a, float b) { f32x2 v = {a, b}; bf16v2_t r = __builtin_convertvector(v, bf16v2_t); return __builtin_bit_cast(unsigned, r); }
; DI float sigm(float x) { return 1.f / (1.f + __expf(-x)); }
;     DI void operator()(const Acc& acc, const Unit& u, int wr, int wc, int fr, int fq, const float (&pre)[8]) const {
;     ...
;                 for (int m = 0; m < 4; ++m) { const size_t o = (size_t)(row0 + ai * HALF + m * 16) * DM + f0 + 4 * n;
;                     const u32x2 xw = *(const u32x2*)(xc + o);
;                     const float xv[4] = {__uint_as_float(xw.x << 16), __uint_as_float(xw.x & 0xffff0000u), __uint_as_float(xw.y << 16), __uint_as_float(xw.y & 0xffff0000u)};
;                     u32x4 w;
; #pragma unroll
;                     for (int e = 0; e < 4; ++e) { const float r = sigm(acc[ai][0][m][n][e] + br[e]), ig = sigm(acc[ai][1][m][n][e] + bi[e]);
;                         const float la = -sp[e] * r, uu = -2.f * la;
;                         const float om = uu * (1.f - uu * 0.5f * (1.f - uu * (1.f / 3.f) * (1.f - uu * 0.25f * (1.f - uu * 0.2f * (1.f - uu * (1.f / 6.f))))));
;                         w[e] = pk2(la, sqrtf(fmaxf(om, 0.f)) * ig * xv[e]); }
;                     *(u32x4*)(ax + o) = w; __builtin_amdgcn_sched_barrier(0); }
	v_mov_b32_e32 v26, v220
	v_mov_b32_e32 v27, v221
	v_and_b32_e32 v28, 0xffff0000, v26
	v_lshlrev_b32_e32 v29, 16, v27
	v_sqrt_f32_e32 v20, v20
	s_nop 0
	v_mul_f32_e32 v16, v16, v20
	v_lshlrev_b32_e32 v20, 16, v26
	v_mul_f32_e32 v16, v16, v20
	v_rcp_f32_e32 v20, v30
	v_and_b32_e32 v33, 0xffff0000, v27
	v_mul_f32_e64 v34, v20, -v65
	v_mul_f32_e32 v20, -2.0, v34
	v_cvt_pk_bf16_f32 v16, v32, v16
	v_mul_f32_e32 v21, 0x3e4ccccd, v20
	v_fma_f32 v157, v20, s81, 1.0
	v_pk_mul_f32 v[26:27], v[20:21], v[156:157]
	v_mul_f32_e32 v35, 0x3eaaaaab, v20
	v_sub_f32_e32 v21, 1.0, v27
	v_fma_f32 v159, -v26, v21, 1.0
	v_mov_b32_e32 v21, v35
	v_pk_mul_f32 v[26:27], v[20:21], v[158:159]
	v_add_f32_e32 v18, v18, v70
	v_sub_f32_e32 v21, 1.0, v27
	v_fma_f32 v21, -v26, v21, 1.0
	v_mul_f32_e32 v20, v20, v21
	v_max_f32_e32 v20, 0, v20
	v_rcp_f32_e32 v17, v17
	v_mul_f32_e32 v18, 0xbfb8aa3b, v18
	v_exp_f32_e32 v18, v18
	v_add_f32_e32 v23, v23, v75
	v_add_f32_e32 v18, 1.0, v18
	v_mul_f32_e32 v23, 0xbfb8aa3b, v23
	v_exp_f32_e32 v23, v23
	v_add_f32_e32 v19, v19, v71
	v_mul_f32_e32 v19, 0xbfb8aa3b, v19
	v_sqrt_f32_e32 v20, v20
	v_add_f32_e32 v21, 1.0, v22
	v_mul_f32_e32 v17, v17, v20
	v_mul_f32_e32 v17, v17, v28
	v_exp_f32_e32 v19, v19
	v_rcp_f32_e32 v20, v21
	s_nop 0
	v_mul_f32_e64 v31, v20, -v66
	v_mul_f32_e32 v20, -2.0, v31
	v_mul_f32_e32 v21, 0x3e4ccccd, v20
	v_fma_f32 v157, v20, s81, 1.0
	v_pk_mul_f32 v[26:27], v[20:21], v[156:157]
	v_mul_f32_e32 v32, 0x3eaaaaab, v20
	v_sub_f32_e32 v21, 1.0, v27
	v_fma_f32 v159, -v26, v21, 1.0
	v_mov_b32_e32 v21, v32
	v_pk_mul_f32 v[26:27], v[20:21], v[158:159]
	v_sub_f32_e32 v21, 1.0, v27
	v_fma_f32 v21, -v26, v21, 1.0
	v_mul_f32_e32 v20, v20, v21
	v_max_f32_e32 v20, 0, v20
	v_rcp_f32_e32 v18, v18
	v_add_f32_e32 v19, 1.0, v19
	v_cvt_pk_bf16_f32 v17, v34, v17
	v_sqrt_f32_e32 v20, v20
	v_add_f32_e32 v21, 1.0, v23
	v_mul_f32_e32 v18, v18, v20
	v_mul_f32_e32 v18, v18, v29
	v_cvt_pk_bf16_f32 v18, v31, v18
	v_rcp_f32_e32 v20, v21
	s_nop 0
	v_mul_f32_e64 v29, v20, -v67
	v_mul_f32_e32 v20, -2.0, v29
	v_mul_f32_e32 v21, 0x3e4ccccd, v20
	v_fma_f32 v157, v20, s81, 1.0
	v_pk_mul_f32 v[22:23], v[20:21], v[156:157]
	v_mul_f32_e32 v30, 0x3eaaaaab, v20
	v_sub_f32_e32 v21, 1.0, v23
	v_fma_f32 v159, -v22, v21, 1.0
	v_mov_b32_e32 v21, v30
	v_pk_mul_f32 v[22:23], v[20:21], v[158:159]
	s_nop 0
	v_sub_f32_e32 v21, 1.0, v23
	v_fma_f32 v21, -v22, v21, 1.0
	v_mul_f32_e32 v20, v20, v21
	v_max_f32_e32 v20, 0, v20
	v_rcp_f32_e32 v19, v19
	v_sqrt_f32_e32 v20, v20
	s_nop 0
	v_mul_f32_e32 v19, v19, v20
	v_mul_f32_e32 v19, v19, v33
	v_cvt_pk_bf16_f32 v19, v29, v19
	v_lshl_add_u64 v[20:21], v[24:25], 2, s[36:37]
	global_store_dwordx4 v[20:21], v[16:19], off
	s_nop 1
	v_lshl_add_u64 v[16:17], v[80:81], 0, v[160:161]
	v_lshl_add_u64 v[18:19], v[16:17], 1, s[16:17]
	v_add_f32_e32 v12, v12, v72
	v_add_f32_e32 v13, v13, v73
	v_mul_f32_e32 v12, 0xbfb8aa3b, v12
	v_mul_f32_e32 v13, 0xbfb8aa3b, v13
	v_exp_f32_e32 v12, v12
	v_exp_f32_e32 v13, v13
	v_add_f32_e32 v8, v8, v68
	v_mul_f32_e32 v8, 0xbfb8aa3b, v8
	v_add_f32_e32 v12, 1.0, v12
	v_add_f32_e32 v22, 1.0, v13
	v_exp_f32_e32 v8, v8
	s_nop 0
	v_add_f32_e32 v8, 1.0, v8
	v_rcp_f32_e32 v12, v12
	s_nop 0
	v_mul_f32_e64 v24, v12, -v64
	v_mul_f32_e32 v12, -2.0, v24
	v_mul_f32_e32 v13, 0x3e4ccccd, v12
	v_fma_f32 v157, v12, s81, 1.0
	v_pk_mul_f32 v[20:21], v[12:13], v[156:157]
	v_mul_f32_e32 v28, 0x3eaaaaab, v12
	v_sub_f32_e32 v21, 1.0, v21
	v_mov_b32_e32 v13, v28
	v_fma_f32 v159, -v20, v21, 1.0
	v_pk_mul_f32 v[20:21], v[12:13], v[158:159]
	v_sub_f32_e32 v13, 1.0, v21
	v_fma_f32 v13, -v20, v13, 1.0
	v_mul_f32_e32 v12, v12, v13
	v_max_f32_e32 v12, 0, v12
	v_rcp_f32_e32 v8, v8
	v_add_f32_e32 v9, v9, v69
	v_mul_f32_e32 v9, 0xbfb8aa3b, v9
	v_exp_f32_e32 v9, v9
	s_nop 0
	v_add_f32_e32 v9, 1.0, v9
	v_add_f32_e32 v14, v14, v74
	v_mul_f32_e32 v14, 0xbfb8aa3b, v14
	v_exp_f32_e32 v14, v14
	s_waitcnt vmcnt(15) lgkmcnt(0)
; DI unsigned pk2(float a, float b) { f32x2 v = {a, b}; bf16v2_t r = __builtin_convertvector(v, bf16v2_t); return __builtin_bit_cast(unsigned, r); }
; DI float sigm(float x) { return 1.f / (1.f + __expf(-x)); }
; template <class Epi, class SchedT>
; DI void gemm_phase(LAS unsigned char* lds, const bf16_t* Ap, const bf16_t* Btp, const int K, const int lda, const SchedT& S, const Epi& E) {
;     ...
;         E(acc, cur, wr, wc, fr, fq, pre);
;         if (!has_next) break;
; #pragma unroll
;         for (int a = 0; a < 2; ++a)
; #pragma unroll
;             for (int b = 0; b < 2; ++b)
; #pragma unroll
;                 for (int m = 0; m < 4; ++m)
; #pragma unroll
;                     for (int n = 0; n < 2; ++n) acc[a][b][m][n] = (f32x4){0.f, 0.f, 0.f, 0.f};
;         cur = nxt; cA = nA; cB = nB; ++ui; E.prefetch(cur, wr, fr, pre);
;     DI void operator()(const Acc& acc, const Unit& u, int wr, int wc, int fr, int fq, const float (&pre)[8]) const {
;     ...
;                 for (int m = 0; m < 4; ++m) { const size_t o = (size_t)(row0 + ai * HALF + m * 16) * DM + f0 + 4 * n;
;                     const u32x2 xw = *(const u32x2*)(xc + o);
;                     const float xv[4] = {__uint_as_float(xw.x << 16), __uint_as_float(xw.x & 0xffff0000u), __uint_as_float(xw.y << 16), __uint_as_float(xw.y & 0xffff0000u)};
;                     u32x4 w;
; #pragma unroll
;                     for (int e = 0; e < 4; ++e) { const float r = sigm(acc[ai][0][m][n][e] + br[e]), ig = sigm(acc[ai][1][m][n][e] + bi[e]);
;                         const float la = -sp[e] * r, uu = -2.f * la;
;                         const float om = uu * (1.f - uu * 0.5f * (1.f - uu * (1.f / 3.f) * (1.f - uu * 0.25f * (1.f - uu * 0.2f * (1.f - uu * (1.f / 6.f))))));
;                         w[e] = pk2(la, sqrtf(fmaxf(om, 0.f)) * ig * xv[e]); }
;                     *(u32x4*)(ax + o) = w; __builtin_amdgcn_sched_barrier(0); }
	v_mov_b32_e32 v18, v222
	v_mov_b32_e32 v19, v223
	v_and_b32_e32 v20, 0xffff0000, v18
	v_lshlrev_b32_e32 v21, 16, v19
	v_sqrt_f32_e32 v12, v12
	s_nop 0
	v_mul_f32_e32 v8, v8, v12
	v_lshlrev_b32_e32 v12, 16, v18
	v_mul_f32_e32 v8, v8, v12
	v_rcp_f32_e32 v12, v22
	v_and_b32_e32 v25, 0xffff0000, v19
	v_mul_f32_e64 v26, v12, -v65
	v_mul_f32_e32 v12, -2.0, v26
	v_cvt_pk_bf16_f32 v8, v24, v8
	v_mul_f32_e32 v13, 0x3e4ccccd, v12
	v_fma_f32 v157, v12, s81, 1.0
	v_pk_mul_f32 v[18:19], v[12:13], v[156:157]
	v_mul_f32_e32 v27, 0x3eaaaaab, v12
	v_sub_f32_e32 v13, 1.0, v19
	v_fma_f32 v159, -v18, v13, 1.0
	v_mov_b32_e32 v13, v27
	v_pk_mul_f32 v[18:19], v[12:13], v[158:159]
	v_add_f32_e32 v10, v10, v70
	v_sub_f32_e32 v13, 1.0, v19
	v_fma_f32 v13, -v18, v13, 1.0
	v_mul_f32_e32 v12, v12, v13
	v_max_f32_e32 v12, 0, v12
	v_rcp_f32_e32 v9, v9
	v_mul_f32_e32 v10, 0xbfb8aa3b, v10
	v_exp_f32_e32 v10, v10
	v_add_f32_e32 v15, v15, v75
	v_add_f32_e32 v10, 1.0, v10
	v_mul_f32_e32 v15, 0xbfb8aa3b, v15
	v_exp_f32_e32 v15, v15
	v_add_f32_e32 v11, v11, v71
	v_mul_f32_e32 v11, 0xbfb8aa3b, v11
	v_sqrt_f32_e32 v12, v12
	v_add_f32_e32 v13, 1.0, v14
	v_mul_f32_e32 v9, v9, v12
	v_mul_f32_e32 v9, v9, v20
	v_exp_f32_e32 v11, v11
	v_rcp_f32_e32 v12, v13
	s_nop 0
	v_mul_f32_e64 v23, v12, -v66
	v_mul_f32_e32 v12, -2.0, v23
	v_mul_f32_e32 v13, 0x3e4ccccd, v12
	v_fma_f32 v157, v12, s81, 1.0
	v_pk_mul_f32 v[18:19], v[12:13], v[156:157]
	v_mul_f32_e32 v24, 0x3eaaaaab, v12
	v_sub_f32_e32 v13, 1.0, v19
	v_fma_f32 v159, -v18, v13, 1.0
	v_mov_b32_e32 v13, v24
	v_pk_mul_f32 v[18:19], v[12:13], v[158:159]
	v_sub_f32_e32 v13, 1.0, v19
	v_fma_f32 v13, -v18, v13, 1.0
	v_mul_f32_e32 v12, v12, v13
	v_max_f32_e32 v12, 0, v12
	v_rcp_f32_e32 v10, v10
	v_add_f32_e32 v11, 1.0, v11
	v_cvt_pk_bf16_f32 v9, v26, v9
	v_sqrt_f32_e32 v12, v12
	v_add_f32_e32 v13, 1.0, v15
	v_mul_f32_e32 v10, v10, v12
	v_mul_f32_e32 v10, v10, v21
	v_cvt_pk_bf16_f32 v10, v23, v10
	v_rcp_f32_e32 v12, v13
	s_nop 0
	v_mul_f32_e64 v21, v12, -v67
	v_mul_f32_e32 v12, -2.0, v21
	v_mul_f32_e32 v13, 0x3e4ccccd, v12
	v_fma_f32 v157, v12, s81, 1.0
	v_pk_mul_f32 v[14:15], v[12:13], v[156:157]
	v_mul_f32_e32 v22, 0x3eaaaaab, v12
	v_sub_f32_e32 v13, 1.0, v15
	v_fma_f32 v159, -v14, v13, 1.0
	v_mov_b32_e32 v13, v22
	v_pk_mul_f32 v[14:15], v[12:13], v[158:159]
	s_nop 0
	v_sub_f32_e32 v13, 1.0, v15
	v_fma_f32 v13, -v14, v13, 1.0
	v_mul_f32_e32 v12, v12, v13
	v_max_f32_e32 v12, 0, v12
	v_rcp_f32_e32 v11, v11
	v_sqrt_f32_e32 v12, v12
	s_nop 0
	v_mul_f32_e32 v11, v11, v12
	v_mul_f32_e32 v11, v11, v25
	v_cvt_pk_bf16_f32 v11, v21, v11
	v_lshl_add_u64 v[12:13], v[16:17], 2, s[36:37]
	global_store_dwordx4 v[12:13], v[8:11], off
	s_nop 1
	v_lshl_add_u64 v[8:9], v[76:77], 0, v[160:161]
	v_lshl_add_u64 v[10:11], v[8:9], 1, s[16:17]
	v_add_f32_e32 v4, v4, v72
	v_add_f32_e32 v5, v5, v73
	v_mul_f32_e32 v4, 0xbfb8aa3b, v4
	v_mul_f32_e32 v5, 0xbfb8aa3b, v5
	v_exp_f32_e32 v4, v4
	v_exp_f32_e32 v5, v5
	v_add_f32_e32 v0, v0, v68
	v_mul_f32_e32 v0, 0xbfb8aa3b, v0
	v_add_f32_e32 v4, 1.0, v4
	v_add_f32_e32 v14, 1.0, v5
	v_exp_f32_e32 v0, v0
	s_nop 0
	v_add_f32_e32 v0, 1.0, v0
	v_rcp_f32_e32 v4, v4
	s_nop 0
	v_mul_f32_e64 v16, v4, -v64
	v_mul_f32_e32 v4, -2.0, v16
	v_mul_f32_e32 v5, 0x3e4ccccd, v4
	v_fma_f32 v157, v4, s81, 1.0
	v_pk_mul_f32 v[12:13], v[4:5], v[156:157]
	v_mul_f32_e32 v20, 0x3eaaaaab, v4
	v_sub_f32_e32 v13, 1.0, v13
	v_mov_b32_e32 v5, v20
	v_fma_f32 v159, -v12, v13, 1.0
	v_pk_mul_f32 v[12:13], v[4:5], v[158:159]
	v_sub_f32_e32 v5, 1.0, v13
	v_fma_f32 v5, -v12, v5, 1.0
	v_mul_f32_e32 v4, v4, v5
	v_max_f32_e32 v4, 0, v4
	v_rcp_f32_e32 v0, v0
	v_add_f32_e32 v1, v1, v69
	v_mul_f32_e32 v1, 0xbfb8aa3b, v1
	v_exp_f32_e32 v1, v1
	s_nop 0
	v_add_f32_e32 v1, 1.0, v1
	v_add_f32_e32 v6, v6, v74
	v_mul_f32_e32 v6, 0xbfb8aa3b, v6
	v_exp_f32_e32 v6, v6
	s_waitcnt vmcnt(15) lgkmcnt(0)
	v_mov_b32_e32 v10, v224
	v_mov_b32_e32 v11, v225
	v_and_b32_e32 v12, 0xffff0000, v10
	v_lshlrev_b32_e32 v13, 16, v11
	v_sqrt_f32_e32 v4, v4
	s_nop 0
	v_mul_f32_e32 v0, v0, v4
	v_lshlrev_b32_e32 v4, 16, v10
	v_mul_f32_e32 v0, v0, v4
	v_rcp_f32_e32 v4, v14
	v_and_b32_e32 v17, 0xffff0000, v11
	v_mul_f32_e64 v18, v4, -v65
	v_mul_f32_e32 v4, -2.0, v18
	v_cvt_pk_bf16_f32 v0, v16, v0
	v_mul_f32_e32 v5, 0x3e4ccccd, v4
	v_fma_f32 v157, v4, s81, 1.0
	v_pk_mul_f32 v[10:11], v[4:5], v[156:157]
	v_mul_f32_e32 v19, 0x3eaaaaab, v4
	v_sub_f32_e32 v5, 1.0, v11
	v_fma_f32 v159, -v10, v5, 1.0
	v_mov_b32_e32 v5, v19
	v_pk_mul_f32 v[10:11], v[4:5], v[158:159]
	v_add_f32_e32 v2, v2, v70
	v_sub_f32_e32 v5, 1.0, v11
	v_fma_f32 v5, -v10, v5, 1.0
	v_mul_f32_e32 v4, v4, v5
	v_max_f32_e32 v4, 0, v4
	v_rcp_f32_e32 v1, v1
	v_mul_f32_e32 v2, 0xbfb8aa3b, v2
	v_exp_f32_e32 v2, v2
	v_add_f32_e32 v7, v7, v75
	v_add_f32_e32 v2, 1.0, v2
	v_mul_f32_e32 v7, 0xbfb8aa3b, v7
	v_exp_f32_e32 v7, v7
	v_add_f32_e32 v3, v3, v71
	v_mul_f32_e32 v3, 0xbfb8aa3b, v3
	v_sqrt_f32_e32 v4, v4
	v_add_f32_e32 v5, 1.0, v6
	v_mul_f32_e32 v1, v1, v4
	v_mul_f32_e32 v1, v1, v12
	v_exp_f32_e32 v3, v3
	v_rcp_f32_e32 v4, v5
	s_nop 0
	v_mul_f32_e64 v15, v4, -v66
	v_mul_f32_e32 v4, -2.0, v15
	v_mul_f32_e32 v5, 0x3e4ccccd, v4
	v_fma_f32 v157, v4, s81, 1.0
	v_pk_mul_f32 v[10:11], v[4:5], v[156:157]
	v_mul_f32_e32 v16, 0x3eaaaaab, v4
	v_sub_f32_e32 v5, 1.0, v11
	v_fma_f32 v159, -v10, v5, 1.0
	v_mov_b32_e32 v5, v16
	v_pk_mul_f32 v[10:11], v[4:5], v[158:159]
	v_sub_f32_e32 v5, 1.0, v11
	v_fma_f32 v5, -v10, v5, 1.0
	v_mul_f32_e32 v4, v4, v5
	v_max_f32_e32 v4, 0, v4
	v_rcp_f32_e32 v2, v2
	v_add_f32_e32 v3, 1.0, v3
	v_cvt_pk_bf16_f32 v1, v18, v1
	v_sqrt_f32_e32 v4, v4
	v_add_f32_e32 v5, 1.0, v7
	v_mul_f32_e32 v2, v2, v4
	v_mul_f32_e32 v2, v2, v13
	v_cvt_pk_bf16_f32 v2, v15, v2
	v_rcp_f32_e32 v4, v5
	s_nop 0
	v_mul_f32_e64 v13, v4, -v67
	v_mul_f32_e32 v4, -2.0, v13
	v_mul_f32_e32 v5, 0x3e4ccccd, v4
	v_fma_f32 v157, v4, s81, 1.0
	v_pk_mul_f32 v[6:7], v[4:5], v[156:157]
	v_mul_f32_e32 v14, 0x3eaaaaab, v4
	v_sub_f32_e32 v5, 1.0, v7
	v_fma_f32 v159, -v6, v5, 1.0
	v_mov_b32_e32 v5, v14
	v_pk_mul_f32 v[6:7], v[4:5], v[158:159]
	s_nop 0
	v_sub_f32_e32 v5, 1.0, v7
	v_fma_f32 v5, -v6, v5, 1.0
	v_mul_f32_e32 v4, v4, v5
	v_max_f32_e32 v4, 0, v4
	v_rcp_f32_e32 v3, v3
	v_sqrt_f32_e32 v4, v4
	s_nop 0
	v_mul_f32_e32 v3, v3, v4
	v_mul_f32_e32 v3, v3, v17
	v_cvt_pk_bf16_f32 v3, v13, v3
	v_lshl_add_u64 v[4:5], v[8:9], 2, s[36:37]
	global_store_dwordx4 v[4:5], v[0:3], off
	s_and_b64 vcc, exec, s[8:9]
	s_mov_b32 s84, s83
	s_mov_b32 s12, s50
	s_mov_b64 s[14:15], s[58:59]
	s_mov_b64 s[60:61], s[56:57]
	s_cbranch_vccnz .LBB0_954
